# ph_mix cross-row software pipeline: it4=0,1 loads issued one row ahead, it4=2,3 + OA/OB at row top
# baseline (speedup 1.0000x reference)
.LBB0_1302:
	s_or_b64 exec, exec, s[40:41]
	s_lshl_b32 s2, s92, 3
	s_add_i32 s38, s2, s93
	s_cmp_ge_i32 s38, s90
	s_waitcnt lgkmcnt(0)
	s_barrier
	s_cbranch_scc1 .LBB0_1306
	v_lshlrev_b32_e32 v0, 2, v10
	v_lshlrev_b32_e32 v2, 3, v10
	s_lshl_b32 s2, s93, 12
	v_ashrrev_i32_e32 v3, 31, v2
	v_add_u32_e32 v4, 0x100, v0
	v_add_u32_e32 v6, 0x200, v0
	v_add_u32_e32 v8, 0x300, v0
	s_add_i32 s2, s2, 0
	s_ashr_i32 s39, s38, 31
	s_lshl_b32 s40, s77, 3
	s_waitcnt vmcnt(27)
	v_lshl_add_u32 v58, v10, 5, 0
	v_ashrrev_i32_e32 v1, 31, v0
	v_lshlrev_b32_e32 v10, 4, v10
	v_ashrrev_i32_e32 v5, 31, v4
	v_ashrrev_i32_e32 v7, 31, v6
	v_ashrrev_i32_e32 v9, 31, v8
	s_add_i32 s2, s2, 0x10000
	s_lshl_b64 s[4:5], s[38:39], 12
	v_lshlrev_b64 v[2:3], 1, v[2:3]
	s_lshl_b64 s[8:9], s[38:39], 10
	v_add_u32_e32 v59, 0, v10
	s_waitcnt vmcnt(26)
	v_add_u32_e32 v60, s2, v10
	v_lshlrev_b64 v[10:11], 1, v[0:1]
	s_ashr_i32 s41, s40, 31
	v_lshl_add_u64 v[14:15], s[4:5], 0, v[2:3]
	v_lshl_add_u64 v[16:17], s[8:9], 0, v[2:3]
	s_lshl_b64 s[8:9], s[38:39], 11
	v_lshl_add_u64 v[20:21], v[0:1], 2, s[4:5]
	v_lshlrev_b64 v[0:1], 1, v[8:9]
	v_lshlrev_b64 v[2:3], 1, v[6:7]
	v_lshlrev_b64 v[4:5], 1, v[4:5]
	v_mov_b32_e32 v6, 0x2e00
	v_lshl_add_u64 v[12:13], s[4:5], 0, v[10:11]
	s_lshl_b64 s[42:43], s[40:41], 12
	s_lshl_b64 s[44:45], s[40:41], 10
	v_lshl_add_u64 v[18:19], s[8:9], 0, v[10:11]
	s_lshl_b64 s[46:47], s[40:41], 11
	v_lshl_add_u64 v[22:23], s[8:9], 0, v[0:1]
	v_lshl_add_u64 v[24:25], s[8:9], 0, v[2:3]
	v_lshl_add_u64 v[26:27], s[8:9], 0, v[4:5]
	v_mad_i64_i32 v[28:29], s[4:5], s38, v6, v[0:1]
	s_mul_i32 s48, s77, 0x17000
	s_mul_hi_i32 s49, s40, 0x2e00
	v_mad_i64_i32 v[30:31], s[4:5], s38, v6, v[2:3]
	v_mad_i64_i32 v[32:33], s[4:5], s38, v6, v[4:5]
	v_mad_i64_i32 v[34:35], s[4:5], s38, v6, v[10:11]
	s_movk_i32 s10, 0x1fff
	s_mov_b32 s11, 0x21401000
	s_mov_b32 s12, 0x2ed00000
	s_mov_b32 s13, 0x21402000
	s_mov_b32 s24, 0x49900000
	s_waitcnt vmcnt(4)
	v_mov_b32_e32 v84, 0x3a27c5ac
	v_mbcnt_lo_u32_b32 v85, -1, 0
	v_mbcnt_hi_u32_b32 v85, -1, v85
	v_lshlrev_b32_e32 v86, 3, v85
	v_lshlrev_b32_e32 v85, 4, v85
	v_add_u32_e32 v87, 0x35100000, v86
	v_add_u32_e32 v88, 0x39300000, v86
	v_add_u32_e32 v86, 0x21401200, v86
	v_add_u32_e32 v85, 0x3b400000, v85
	s_cmpk_lt_i32 s38, 0x4000
	s_cselect_b32 s2, s10, 0xff
	s_and_b32 s6, s2, s38
	s_cmp_eq_u32 s6, 0
	s_cselect_b32 s4, 0, 0xffffd200
	s_cmp_eq_u32 s6, s2
	s_cselect_b32 s5, 0, 0x2e00
	s_mul_i32 s2, s38, 0x2e00
	v_add_u32_e32 v91, s2, v86
	s_lshl_b32 s2, s38, 12
	v_add_u32_e32 v89, s2, v85
	s_lshl_b32 s2, s38, 11
	v_add_u32_e32 v97, s2, v87
	v_add_u32_e32 v99, s2, v88
	v_add_u32_e32 v90, 0x4200000, v89
	v_add_u32_e32 v98, 0x2100000, v97
	v_add_u32_e32 v92, 0x1000, v91
	v_add_u32_e32 v93, s4, v91
	v_add_u32_e32 v95, s5, v91
	v_add_u32_e32 v94, 0x1000, v93
	v_add_u32_e32 v96, 0x1000, v95
	global_load_dwordx4 v[100:103], v89, s[74:75]
	global_load_dwordx4 v[104:107], v90, s[74:75]
	global_load_dwordx2 v[108:109], v91, s[74:75]
	global_load_dwordx2 v[110:111], v92, s[74:75]
	global_load_dwordx2 v[112:113], v91, s[74:75] offset:2048
	global_load_dwordx2 v[114:115], v93, s[74:75]
	global_load_dwordx2 v[116:117], v94, s[74:75]
	global_load_dwordx2 v[118:119], v93, s[74:75] offset:2048
	global_load_dwordx2 v[120:121], v97, s[74:75]
	global_load_dwordx2 v[122:123], v95, s[74:75]
	global_load_dwordx2 v[124:125], v96, s[74:75]
	global_load_dwordx2 v[126:127], v95, s[74:75] offset:2048
	global_load_dwordx2 v[128:129], v98, s[74:75]
	global_load_dwordx2 v[130:131], v99, s[74:75]
	global_load_dwordx4 v[132:135], v89, s[74:75] offset:1024
	global_load_dwordx4 v[136:139], v90, s[74:75] offset:1024
	global_load_dwordx2 v[140:141], v91, s[74:75] offset:512
	global_load_dwordx2 v[142:143], v92, s[74:75] offset:512
	global_load_dwordx2 v[144:145], v91, s[74:75] offset:2560
	global_load_dwordx2 v[146:147], v93, s[74:75] offset:512
	global_load_dwordx2 v[148:149], v94, s[74:75] offset:512
	global_load_dwordx2 v[150:151], v93, s[74:75] offset:2560
	global_load_dwordx2 v[152:153], v97, s[74:75] offset:512
	global_load_dwordx2 v[154:155], v95, s[74:75] offset:512
	global_load_dwordx2 v[156:157], v96, s[74:75] offset:512
	global_load_dwordx2 v[158:159], v95, s[74:75] offset:2560
	global_load_dwordx2 v[160:161], v98, s[74:75] offset:512
	global_load_dwordx2 v[162:163], v99, s[74:75] offset:512
	global_load_dword v236, v85, s[74:75]
	global_load_dword v236, v85, s[74:75]
	global_load_dword v236, v85, s[74:75]
	global_load_dword v236, v85, s[74:75]
	global_load_dword v236, v85, s[74:75]
	global_load_dword v236, v85, s[74:75]
.LBB0_1304:
	s_lshl_b32 s2, s38, 10
	s_add_u32 s2, s2, 0xf3900000
	v_add_u32_e32 v230, s2, v85
	v_add_u32_e32 v231, 0x1100000, v230
	global_load_dwordx4 v[164:167], v89, s[74:75] offset:2048
	global_load_dwordx4 v[168:171], v90, s[74:75] offset:2048
	global_load_dwordx2 v[172:173], v91, s[74:75] offset:1024
	global_load_dwordx2 v[174:175], v92, s[74:75] offset:1024
	global_load_dwordx2 v[176:177], v91, s[74:75] offset:3072
	global_load_dwordx2 v[178:179], v93, s[74:75] offset:1024
	global_load_dwordx2 v[180:181], v94, s[74:75] offset:1024
	global_load_dwordx2 v[182:183], v93, s[74:75] offset:3072
	global_load_dwordx2 v[184:185], v97, s[74:75] offset:1024
	global_load_dwordx2 v[186:187], v95, s[74:75] offset:1024
	global_load_dwordx2 v[188:189], v96, s[74:75] offset:1024
	global_load_dwordx2 v[190:191], v95, s[74:75] offset:3072
	global_load_dwordx2 v[192:193], v98, s[74:75] offset:1024
	global_load_dwordx2 v[194:195], v99, s[74:75] offset:1024
	global_load_dwordx4 v[196:199], v89, s[74:75] offset:3072
	global_load_dwordx4 v[200:203], v90, s[74:75] offset:3072
	global_load_dwordx2 v[204:205], v91, s[74:75] offset:1536
	global_load_dwordx2 v[206:207], v92, s[74:75] offset:1536
	global_load_dwordx2 v[210:211], v91, s[74:75] offset:3584
	global_load_dwordx2 v[212:213], v93, s[74:75] offset:1536
	global_load_dwordx2 v[214:215], v94, s[74:75] offset:1536
	global_load_dwordx2 v[216:217], v93, s[74:75] offset:3584
	global_load_dwordx2 v[218:219], v99, s[74:75] offset:1536
	global_load_dwordx2 v[220:221], v97, s[74:75] offset:1536
	global_load_dwordx2 v[222:223], v95, s[74:75] offset:1536
	global_load_dwordx2 v[224:225], v96, s[74:75] offset:1536
	global_load_dwordx2 v[226:227], v95, s[74:75] offset:3584
	global_load_dwordx2 v[228:229], v98, s[74:75] offset:1536
	global_load_dwordx4 v[232:235], v230, s[74:75]
	s_add_i32 s8, s38, s40
	s_cmpk_lt_i32 s8, 0x4000
	s_cselect_b32 s2, s10, 0xff
	s_and_b32 s6, s2, s8
	s_cmp_eq_u32 s6, 0
	s_cselect_b32 s4, 0, 0xffffd200
	s_cmp_eq_u32 s6, s2
	s_cselect_b32 s5, 0, 0x2e00
	s_mul_i32 s2, s8, 0x2e00
	v_add_u32_e32 v91, s2, v86
	s_lshl_b32 s2, s8, 12
	v_add_u32_e32 v89, s2, v85
	s_lshl_b32 s2, s8, 11
	v_add_u32_e32 v97, s2, v87
	v_add_u32_e32 v99, s2, v88
	v_add_u32_e32 v90, 0x4200000, v89
	v_add_u32_e32 v98, 0x2100000, v97
	v_add_u32_e32 v92, 0x1000, v91
	v_add_u32_e32 v93, s4, v91
	v_add_u32_e32 v95, s5, v91
	v_add_u32_e32 v94, 0x1000, v93
	v_add_u32_e32 v96, 0x1000, v95
	s_cmpk_lt_i32 s38, 0x4000
	s_cselect_b32 s2, s10, 0xff
	s_and_b32 s6, s2, s38
	s_cmp_eq_u32 s6, 0
	s_cselect_b64 s[52:53], -1, 0
	s_and_b64 s[4:5], s[52:53], exec
	s_cselect_b32 s4, 0, 0xffffd200
	s_cselect_b32 s5, 0, -1
	s_cmp_eq_u32 s6, s2
	v_lshl_add_u64 v[4:5], s[74:75], 0, v[20:21]
	s_mov_b32 s6, 0x3b400000
	v_add_co_u32_e32 v36, vcc, s6, v4
	s_mov_b32 s6, 0x3f600000
	s_nop 0
	v_addc_co_u32_e32 v37, vcc, 0, v5, vcc
	v_add_co_u32_e32 v38, vcc, s6, v4
	s_waitcnt vmcnt(62)
	v_mov_b32_e32 v0, v100
	v_mov_b32_e32 v1, v101
	v_mov_b32_e32 v2, v102
	v_mov_b32_e32 v3, v103
	global_load_dwordx4 v[240:243], v231, s[74:75]
	s_nop 0
	v_addc_co_u32_e32 v39, vcc, 0, v5, vcc
	s_waitcnt vmcnt(62)
	v_mov_b32_e32 v4, v104
	v_mov_b32_e32 v5, v105
	v_mov_b32_e32 v6, v106
	v_mov_b32_e32 v7, v107
	s_cselect_b64 s[50:51], -1, 0
	s_and_b64 s[8:9], s[50:51], exec
	s_cselect_b32 s2, 0, 0x2e00
	s_add_u32 s54, s74, s4
	s_addc_u32 s55, s75, s5
	v_lshl_add_u64 v[44:45], s[54:55], 0, v[34:35]
	s_add_u32 s56, s74, s2
	s_addc_u32 s57, s75, 0
	s_mov_b32 s2, 0x39300000
	s_add_i32 s38, s38, s40
	v_lshl_add_u64 v[20:21], v[20:21], 0, s[42:43]
	s_cmp_lt_i32 s38, s90
	v_pk_add_f32 v[2:3], v[2:3], v[6:7]
	v_pk_add_f32 v[0:1], v[0:1], v[4:5]
	v_mov_b32_e32 v7, v3
	v_pk_mov_b32 v[4:5], v[0:1], v[2:3] op_sel:[1,0]
	v_mov_b32_e32 v6, v0
	v_pk_add_f32 v[4:5], v[4:5], v[6:7]
	s_nop 0
	v_add_f32_e32 v4, v4, v5
	s_nop 1
	v_add_f32_dpp v4, v4, v4 quad_perm:[1,0,3,2] row_mask:0xf bank_mask:0xf bound_ctrl:1
	s_nop 1
	v_add_f32_dpp v4, v4, v4 quad_perm:[2,3,0,1] row_mask:0xf bank_mask:0xf bound_ctrl:1
	s_nop 1
	v_add_f32_dpp v4, v4, v4 row_half_mirror row_mask:0xf bank_mask:0xf bound_ctrl:1
	s_nop 1
	v_add_f32_dpp v4, v4, v4 row_mirror row_mask:0xf bank_mask:0xf bound_ctrl:1
	v_fmamk_f32 v1, v4, 0xbc800000, v1
	v_fmac_f32_e32 v0, 0xbc800000, v4
	v_fmamk_f32 v3, v4, 0xbc800000, v3
	v_fmac_f32_e32 v2, 0xbc800000, v4
	v_pk_mul_f32 v[4:5], v[2:3], v[2:3]
	v_pk_mul_f32 v[6:7], v[0:1], v[0:1]
	s_nop 0
	v_pk_mov_b32 v[8:9], v[6:7], v[4:5] op_sel:[1,0]
	v_mov_b32_e32 v7, v5
	v_pk_add_f32 v[4:5], v[8:9], v[6:7]
	s_nop 0
	v_add_f32_e32 v4, v4, v5
	s_nop 1
	v_add_f32_dpp v4, v4, v4 quad_perm:[1,0,3,2] row_mask:0xf bank_mask:0xf bound_ctrl:1
	s_nop 1
	v_add_f32_dpp v4, v4, v4 quad_perm:[2,3,0,1] row_mask:0xf bank_mask:0xf bound_ctrl:1
	s_nop 1
	v_add_f32_dpp v4, v4, v4 row_half_mirror row_mask:0xf bank_mask:0xf bound_ctrl:1
	s_nop 1
	v_add_f32_dpp v4, v4, v4 row_mirror row_mask:0xf bank_mask:0xf bound_ctrl:1
	v_fmamk_f32 v4, v4, 0x3c800000, v84
	v_rsq_f32_e32 v4, v4
	s_nop 0
	v_pk_mul_f32 v[8:9], v[2:3], v[4:5] op_sel_hi:[1,0]
	v_pk_mul_f32 v[10:11], v[0:1], v[4:5] op_sel_hi:[1,0]
	ds_read_b128 v[0:3], v59
	ds_read_b128 v[4:7], v59 offset:4096
	s_waitcnt lgkmcnt(0)
	v_pk_fma_f32 v[0:1], v[0:1], v[10:11], v[4:5]
	v_lshl_add_u64 v[4:5], s[74:75], 0, v[34:35]
	v_pk_fma_f32 v[2:3], v[2:3], v[8:9], v[6:7]
	v_add_co_u32_e32 v6, vcc, s11, v4
	s_nop 1
	v_addc_co_u32_e32 v7, vcc, 0, v5, vcc
	v_add_co_u32_e32 v4, vcc, s13, v4
	s_waitcnt vmcnt(61)
	v_mov_b32_e32 v8, v108
	v_mov_b32_e32 v9, v109
	s_nop 0
	v_addc_co_u32_e32 v5, vcc, 0, v5, vcc
	s_waitcnt vmcnt(60)
	v_mov_b32_e32 v4, v110
	v_mov_b32_e32 v5, v111
	v_add_co_u32_e32 v46, vcc, s11, v44
	s_waitcnt vmcnt(59)
	v_mov_b32_e32 v6, v112
	v_mov_b32_e32 v7, v113
	s_nop 0
	v_addc_co_u32_e32 v47, vcc, 0, v45, vcc
	v_add_co_u32_e32 v44, vcc, s13, v44
	v_lshlrev_b32_e32 v10, 16, v8
	v_addc_co_u32_e32 v45, vcc, 0, v45, vcc
	v_and_b32_e32 v11, 0xffff0000, v8
	v_lshlrev_b32_e32 v48, 16, v9
	v_and_b32_e32 v49, 0xffff0000, v9
	v_lshlrev_b32_e32 v50, 16, v6
	v_and_b32_e32 v51, 0xffff0000, v6
	v_lshlrev_b32_e32 v52, 16, v7
	v_and_b32_e32 v53, 0xffff0000, v7
	ds_read_b128 v[6:9], v59 offset:8192
	ds_read_b128 v[40:43], v59 offset:12288
	s_waitcnt vmcnt(58)
	v_mov_b32_e32 v62, v114
	v_mov_b32_e32 v63, v115
	v_lshlrev_b32_e32 v56, 16, v5
	s_waitcnt vmcnt(57)
	v_mov_b32_e32 v44, v116
	v_mov_b32_e32 v45, v117
	v_and_b32_e32 v57, 0xffff0000, v5
	s_waitcnt vmcnt(56)
	v_mov_b32_e32 v46, v118
	v_mov_b32_e32 v47, v119
	v_lshlrev_b32_e32 v54, 16, v4
	v_and_b32_e32 v55, 0xffff0000, v4
	v_lshl_add_u64 v[4:5], s[74:75], 0, v[18:19]
	v_lshl_add_u64 v[18:19], v[18:19], 0, s[46:47]
	v_lshlrev_b32_e32 v61, 16, v62
	v_and_b32_e32 v62, 0xffff0000, v62
	v_lshlrev_b32_e32 v67, 16, v44
	v_and_b32_e32 v44, 0xffff0000, v44
	v_lshlrev_b32_e32 v65, 16, v46
	v_and_b32_e32 v46, 0xffff0000, v46
	v_lshlrev_b32_e32 v66, 16, v47
	v_and_b32_e32 v47, 0xffff0000, v47
	v_lshlrev_b32_e32 v68, 16, v45
	v_and_b32_e32 v45, 0xffff0000, v45
	v_cndmask_b32_e64 v72, v67, 0, s[52:53]
	v_cndmask_b32_e64 v73, v44, 0, s[52:53]
	v_cndmask_b32_e64 v71, v45, 0, s[52:53]
	v_cndmask_b32_e64 v69, v46, 0, s[52:53]
	v_cndmask_b32_e64 v67, v47, 0, s[52:53]
	ds_read_b128 v[44:47], v59 offset:16384
	v_lshlrev_b32_e32 v64, 16, v63
	v_and_b32_e32 v63, 0xffff0000, v63
	v_cndmask_b32_e64 v70, v68, 0, s[52:53]
	v_cndmask_b32_e64 v68, v65, 0, s[52:53]
	v_cndmask_b32_e64 v64, v64, 0, s[52:53]
	v_cndmask_b32_e64 v65, v63, 0, s[52:53]
	v_cndmask_b32_e64 v61, v61, 0, s[52:53]
	v_cndmask_b32_e64 v62, v62, 0, s[52:53]
	v_sub_f32_e32 v63, v62, v11
	v_sub_f32_e32 v62, v61, v10
	v_sub_f32_e32 v65, v65, v49
	v_sub_f32_e32 v64, v64, v48
	s_waitcnt lgkmcnt(0)
	v_pk_fma_f32 v[64:65], v[46:47], v[64:65], v[48:49]
	v_pk_fma_f32 v[62:63], v[44:45], v[62:63], v[10:11]
	ds_read_b128 v[44:47], v59 offset:20480
	v_cndmask_b32_e64 v66, v66, 0, s[52:53]
	v_sub_f32_e32 v67, v67, v53
	v_sub_f32_e32 v66, v66, v52
	v_sub_f32_e32 v69, v69, v51
	v_sub_f32_e32 v68, v68, v50
	s_waitcnt lgkmcnt(0)
	v_pk_fma_f32 v[68:69], v[44:45], v[68:69], v[50:51]
	v_pk_fma_f32 v[66:67], v[46:47], v[66:67], v[52:53]
	ds_read_b128 v[44:47], v59 offset:24576
	v_sub_f32_e32 v71, v71, v57
	v_sub_f32_e32 v70, v70, v56
	v_sub_f32_e32 v73, v73, v55
	v_sub_f32_e32 v72, v72, v54
	s_waitcnt lgkmcnt(0)
	v_pk_fma_f32 v[46:47], v[46:47], v[70:71], v[56:57]
	v_add_co_u32_e32 v70, vcc, s97, v4
	v_pk_fma_f32 v[44:45], v[44:45], v[72:73], v[54:55]
	s_nop 0
	v_addc_co_u32_e32 v71, vcc, 0, v5, vcc
	s_waitcnt vmcnt(55)
	v_mov_b32_e32 v70, v120
	v_mov_b32_e32 v71, v121
	v_lshlrev_b32_e32 v72, 16, v70
	v_and_b32_e32 v73, 0xffff0000, v70
	v_lshlrev_b32_e32 v70, 16, v71
	v_and_b32_e32 v71, 0xffff0000, v71
	v_pk_add_f32 v[70:71], v[70:71], -1.0 op_sel_hi:[1,0]
	v_pk_add_f32 v[72:73], v[72:73], -1.0 op_sel_hi:[1,0]
	v_pk_fma_f32 v[70:71], v[42:43], v[70:71], 1.0 op_sel_hi:[1,1,0]
	v_pk_fma_f32 v[72:73], v[40:41], v[72:73], 1.0 op_sel_hi:[1,1,0]
	v_pk_mul_f32 v[66:67], v[66:67], v[70:71]
	v_pk_mul_f32 v[68:69], v[68:69], v[72:73]
	v_pk_mul_f32 v[64:65], v[64:65], v[66:67]
	v_pk_mul_f32 v[62:63], v[62:63], v[68:69]
	v_pk_mul_f32 v[64:65], v[8:9], v[64:65]
	v_pk_mul_f32 v[62:63], v[6:7], v[62:63]
	s_nop 0
	v_pk_mov_b32 v[66:67], v[62:63], v[64:65] op_sel:[1,0]
	v_mov_b32_e32 v63, v65
	v_pk_add_f32 v[62:63], v[66:67], v[62:63]
	s_nop 0
	v_add_f32_e32 v61, v62, v63
	s_nop 1
	v_add_f32_dpp v61, v61, v61 quad_perm:[1,0,3,2] row_mask:0xf bank_mask:0xf bound_ctrl:1
	s_nop 1
	v_add_f32_dpp v61, v61, v61 quad_perm:[2,3,0,1] row_mask:0xf bank_mask:0xf bound_ctrl:1
	s_nop 1
	v_add_f32_dpp v61, v61, v61 row_half_mirror row_mask:0xf bank_mask:0xf bound_ctrl:1
	s_nop 1
	v_add_f32_dpp v62, v61, v61 row_mirror row_mask:0xf bank_mask:0xf bound_ctrl:1
	v_pk_fma_f32 v[44:45], v[44:45], v[62:63], v[0:1] op_sel_hi:[1,0,1]
	v_lshl_add_u64 v[0:1], s[56:57], 0, v[34:35]
	v_pk_fma_f32 v[46:47], v[46:47], v[62:63], v[2:3] op_sel_hi:[1,0,1]
	v_add_co_u32_e32 v2, vcc, s11, v0
	v_lshl_add_u64 v[34:35], v[34:35], 0, s[48:49]
	s_nop 0
	v_addc_co_u32_e32 v3, vcc, 0, v1, vcc
	v_add_co_u32_e32 v0, vcc, s13, v0
	s_waitcnt vmcnt(54)
	v_mov_b32_e32 v62, v122
	v_mov_b32_e32 v63, v123
	s_nop 0
	v_addc_co_u32_e32 v1, vcc, 0, v1, vcc
	s_waitcnt vmcnt(53)
	v_mov_b32_e32 v0, v124
	v_mov_b32_e32 v1, v125
	v_lshlrev_b32_e32 v61, 16, v62
	s_waitcnt vmcnt(52)
	v_mov_b32_e32 v2, v126
	v_mov_b32_e32 v3, v127
	v_and_b32_e32 v62, 0xffff0000, v62
	v_lshlrev_b32_e32 v67, 16, v0
	v_and_b32_e32 v0, 0xffff0000, v0
	v_lshlrev_b32_e32 v68, 16, v1
	v_and_b32_e32 v1, 0xffff0000, v1
	v_cndmask_b32_e64 v69, v1, 0, s[50:51]
	v_cndmask_b32_e64 v70, v0, 0, s[50:51]
	v_lshlrev_b32_e32 v64, 16, v63
	v_and_b32_e32 v63, 0xffff0000, v63
	v_cndmask_b32_e64 v64, v64, 0, s[50:51]
	v_cndmask_b32_e64 v61, v61, 0, s[50:51]
	v_cndmask_b32_e64 v62, v62, 0, s[50:51]
	v_sub_f32_e32 v64, v64, v48
	v_cndmask_b32_e64 v67, v67, 0, s[50:51]
	v_cndmask_b32_e64 v68, v68, 0, s[50:51]
	v_lshlrev_b32_e32 v65, 16, v2
	v_and_b32_e32 v2, 0xffff0000, v2
	v_lshlrev_b32_e32 v66, 16, v3
	v_and_b32_e32 v3, 0xffff0000, v3
	v_cndmask_b32_e64 v72, v2, 0, s[50:51]
	v_cndmask_b32_e64 v73, v3, 0, s[50:51]
	ds_read_b128 v[0:3], v59 offset:28672
	v_cndmask_b32_e64 v71, v65, 0, s[50:51]
	v_cndmask_b32_e64 v65, v63, 0, s[50:51]
	v_sub_f32_e32 v63, v62, v11
	v_sub_f32_e32 v62, v61, v10
	v_sub_f32_e32 v65, v65, v49
	s_waitcnt lgkmcnt(0)
	v_pk_fma_f32 v[48:49], v[2:3], v[64:65], v[48:49]
	v_pk_fma_f32 v[10:11], v[0:1], v[62:63], v[10:11]
	ds_read_b128 v[0:3], v59 offset:32768
	v_cndmask_b32_e64 v66, v66, 0, s[50:51]
	v_sub_f32_e32 v63, v73, v53
	v_sub_f32_e32 v62, v66, v52
	v_sub_f32_e32 v65, v72, v51
	v_sub_f32_e32 v64, v71, v50
	s_waitcnt lgkmcnt(0)
	v_pk_fma_f32 v[50:51], v[0:1], v[64:65], v[50:51]
	v_pk_fma_f32 v[52:53], v[2:3], v[62:63], v[52:53]
	ds_read_b128 v[0:3], v59 offset:36864
	v_sub_f32_e32 v63, v70, v55
	v_sub_f32_e32 v62, v67, v54
	v_sub_f32_e32 v65, v69, v57
	v_sub_f32_e32 v64, v68, v56
	s_waitcnt lgkmcnt(0)
	v_pk_fma_f32 v[0:1], v[0:1], v[62:63], v[54:55]
	v_add_co_u32_e32 v54, vcc, s70, v4
	v_pk_fma_f32 v[2:3], v[2:3], v[64:65], v[56:57]
	s_nop 0
	v_addc_co_u32_e32 v55, vcc, 0, v5, vcc
	s_waitcnt vmcnt(51)
	v_mov_b32_e32 v54, v128
	v_mov_b32_e32 v55, v129
	v_lshl_add_u64 v[62:63], s[54:55], 0, v[32:33]
	v_lshlrev_b32_e32 v56, 16, v54
	v_and_b32_e32 v57, 0xffff0000, v54
	v_lshlrev_b32_e32 v54, 16, v55
	v_and_b32_e32 v55, 0xffff0000, v55
	v_pk_add_f32 v[54:55], v[54:55], -1.0 op_sel_hi:[1,0]
	v_pk_add_f32 v[56:57], v[56:57], -1.0 op_sel_hi:[1,0]
	v_pk_fma_f32 v[42:43], v[42:43], v[54:55], 1.0 op_sel_hi:[1,1,0]
	v_pk_fma_f32 v[40:41], v[40:41], v[56:57], 1.0 op_sel_hi:[1,1,0]
	v_pk_mul_f32 v[42:43], v[52:53], v[42:43]
	v_pk_mul_f32 v[40:41], v[50:51], v[40:41]
	v_lshl_add_u64 v[52:53], s[74:75], 0, v[26:27]
	v_pk_mul_f32 v[10:11], v[10:11], v[40:41]
	v_pk_mul_f32 v[40:41], v[48:49], v[42:43]
	v_pk_mul_f32 v[6:7], v[6:7], v[10:11]
	v_pk_mul_f32 v[8:9], v[8:9], v[40:41]
	v_lshl_add_u64 v[26:27], v[26:27], 0, s[46:47]
	v_pk_mov_b32 v[10:11], v[6:7], v[8:9] op_sel:[1,0]
	v_add_co_u32_e32 v8, vcc, s2, v4
	v_mov_b32_e32 v7, v9
	s_nop 0
	v_addc_co_u32_e32 v9, vcc, 0, v5, vcc
	s_waitcnt vmcnt(50)
	v_mov_b32_e32 v4, v130
	v_mov_b32_e32 v5, v131
	v_pk_add_f32 v[6:7], v[10:11], v[6:7]
	s_nop 0
	v_add_f32_e32 v6, v6, v7
	s_nop 1
	v_add_f32_dpp v6, v6, v6 quad_perm:[1,0,3,2] row_mask:0xf bank_mask:0xf bound_ctrl:1
	s_nop 1
	v_add_f32_dpp v6, v6, v6 quad_perm:[2,3,0,1] row_mask:0xf bank_mask:0xf bound_ctrl:1
	s_nop 1
	v_add_f32_dpp v6, v6, v6 row_half_mirror row_mask:0xf bank_mask:0xf bound_ctrl:1
	s_nop 1
	v_add_f32_dpp v6, v6, v6 row_mirror row_mask:0xf bank_mask:0xf bound_ctrl:1
	v_pk_fma_f32 v[0:1], v[0:1], v[6:7], v[44:45] op_sel_hi:[1,0,1]
	v_pk_fma_f32 v[2:3], v[2:3], v[6:7], v[46:47] op_sel_hi:[1,0,1]
	v_lshlrev_b32_e32 v6, 16, v4
	v_and_b32_e32 v7, 0xffff0000, v4
	v_lshlrev_b32_e32 v4, 16, v5
	v_and_b32_e32 v5, 0xffff0000, v5
	v_pk_mul_f32 v[2:3], v[2:3], v[4:5]
	v_pk_mul_f32 v[0:1], v[0:1], v[6:7]
	ds_write_b128 v60, v[0:3]
	v_pk_mul_f32 v[2:3], v[2:3], v[2:3]
	v_pk_mul_f32 v[0:1], v[0:1], v[0:1]
	s_nop 0
	v_pk_mov_b32 v[4:5], v[0:1], v[2:3] op_sel:[1,0]
	v_mov_b32_e32 v1, v3
	v_pk_add_f32 v[0:1], v[4:5], v[0:1]
	s_nop 0
	v_pk_add_f32 v[10:11], v[0:1], v[0:1] op_sel:[0,1] op_sel_hi:[1,0]
	s_waitcnt vmcnt(49)
	v_mov_b32_e32 v0, v132
	v_mov_b32_e32 v1, v133
	v_mov_b32_e32 v2, v134
	v_mov_b32_e32 v3, v135
	s_waitcnt vmcnt(48)
	v_mov_b32_e32 v4, v136
	v_mov_b32_e32 v5, v137
	v_mov_b32_e32 v6, v138
	v_mov_b32_e32 v7, v139
	v_pk_add_f32 v[2:3], v[2:3], v[6:7]
	v_pk_add_f32 v[4:5], v[0:1], v[4:5]
	v_mov_b32_e32 v7, v3
	v_pk_mov_b32 v[0:1], v[4:5], v[2:3] op_sel:[1,0]
	v_mov_b32_e32 v6, v4
	v_pk_add_f32 v[0:1], v[0:1], v[6:7]
	s_nop 0
	v_add_f32_e32 v0, v0, v1
	s_nop 1
	v_add_f32_dpp v0, v0, v0 quad_perm:[1,0,3,2] row_mask:0xf bank_mask:0xf bound_ctrl:1
	s_nop 1
	v_add_f32_dpp v0, v0, v0 quad_perm:[2,3,0,1] row_mask:0xf bank_mask:0xf bound_ctrl:1
	s_nop 1
	v_add_f32_dpp v0, v0, v0 row_half_mirror row_mask:0xf bank_mask:0xf bound_ctrl:1
	s_nop 1
	v_add_f32_dpp v0, v0, v0 row_mirror row_mask:0xf bank_mask:0xf bound_ctrl:1
	v_fmamk_f32 v5, v0, 0xbc800000, v5
	v_fmac_f32_e32 v4, 0xbc800000, v0
	v_fmamk_f32 v3, v0, 0xbc800000, v3
	v_fmac_f32_e32 v2, 0xbc800000, v0
	v_pk_mul_f32 v[0:1], v[2:3], v[2:3]
	v_pk_mul_f32 v[6:7], v[4:5], v[4:5]
	s_nop 0
	v_pk_mov_b32 v[40:41], v[6:7], v[0:1] op_sel:[1,0]
	v_mov_b32_e32 v7, v1
	v_pk_add_f32 v[0:1], v[40:41], v[6:7]
	s_nop 0
	v_add_f32_e32 v0, v0, v1
	s_nop 1
	v_add_f32_dpp v0, v0, v0 quad_perm:[1,0,3,2] row_mask:0xf bank_mask:0xf bound_ctrl:1
	s_nop 1
	v_add_f32_dpp v0, v0, v0 quad_perm:[2,3,0,1] row_mask:0xf bank_mask:0xf bound_ctrl:1
	s_nop 1
	v_add_f32_dpp v0, v0, v0 row_half_mirror row_mask:0xf bank_mask:0xf bound_ctrl:1
	s_nop 1
	v_add_f32_dpp v0, v0, v0 row_mirror row_mask:0xf bank_mask:0xf bound_ctrl:1
	v_fmamk_f32 v0, v0, 0x3c800000, v84
	v_rsq_f32_e32 v6, v0
	s_nop 0
	v_pk_mul_f32 v[0:1], v[2:3], v[6:7] op_sel_hi:[1,0]
	v_pk_mul_f32 v[2:3], v[4:5], v[6:7] op_sel_hi:[1,0]
	ds_read_b128 v[4:7], v59 offset:1024
	ds_read_b128 v[40:43], v59 offset:5120
	s_waitcnt lgkmcnt(0)
	v_pk_fma_f32 v[56:57], v[6:7], v[0:1], v[42:43]
	v_lshl_add_u64 v[0:1], s[74:75], 0, v[32:33]
	v_pk_fma_f32 v[54:55], v[4:5], v[2:3], v[40:41]
	v_add_co_u32_e32 v2, vcc, s11, v0
	s_nop 1
	v_addc_co_u32_e32 v3, vcc, 0, v1, vcc
	v_add_co_u32_e32 v0, vcc, s13, v0
	s_waitcnt vmcnt(47)
	v_mov_b32_e32 v4, v140
	v_mov_b32_e32 v5, v141
	s_nop 0
	v_addc_co_u32_e32 v1, vcc, 0, v1, vcc
	s_waitcnt vmcnt(46)
	v_mov_b32_e32 v0, v142
	v_mov_b32_e32 v1, v143
	v_add_co_u32_e32 v64, vcc, s11, v62
	s_waitcnt vmcnt(45)
	v_mov_b32_e32 v2, v144
	v_mov_b32_e32 v3, v145
	s_nop 0
	v_addc_co_u32_e32 v65, vcc, 0, v63, vcc
	v_add_co_u32_e32 v62, vcc, s13, v62
	v_lshlrev_b32_e32 v48, 16, v4
	v_addc_co_u32_e32 v63, vcc, 0, v63, vcc
	v_and_b32_e32 v49, 0xffff0000, v4
	v_lshlrev_b32_e32 v50, 16, v5
	v_and_b32_e32 v51, 0xffff0000, v5
	v_lshlrev_b32_e32 v44, 16, v2
	v_and_b32_e32 v45, 0xffff0000, v2
	v_lshlrev_b32_e32 v46, 16, v3
	v_and_b32_e32 v47, 0xffff0000, v3
	v_lshlrev_b32_e32 v40, 16, v0
	v_and_b32_e32 v41, 0xffff0000, v0
	v_lshlrev_b32_e32 v42, 16, v1
	v_and_b32_e32 v43, 0xffff0000, v1
	ds_read_b128 v[0:3], v59 offset:9216
	ds_read_b128 v[4:7], v59 offset:13312
	s_waitcnt vmcnt(44)
	v_mov_b32_e32 v66, v146
	v_mov_b32_e32 v67, v147
	s_nop 0
	s_waitcnt vmcnt(43)
	v_mov_b32_e32 v62, v148
	v_mov_b32_e32 v63, v149
	v_lshlrev_b32_e32 v11, 16, v66
	s_waitcnt vmcnt(42)
	v_mov_b32_e32 v64, v150
	v_mov_b32_e32 v65, v151
	v_lshlrev_b32_e32 v70, 16, v62
	v_and_b32_e32 v62, 0xffff0000, v62
	v_lshlrev_b32_e32 v71, 16, v63
	v_and_b32_e32 v63, 0xffff0000, v63
	v_cndmask_b32_e64 v77, v62, 0, s[52:53]
	v_cndmask_b32_e64 v74, v71, 0, s[52:53]
	v_cndmask_b32_e64 v75, v63, 0, s[52:53]
	v_and_b32_e32 v61, 0xffff0000, v66
	v_lshlrev_b32_e32 v66, 16, v67
	v_and_b32_e32 v67, 0xffff0000, v67
	v_cndmask_b32_e64 v76, v70, 0, s[52:53]
	v_cndmask_b32_e64 v11, v11, 0, s[52:53]
	v_cndmask_b32_e64 v61, v61, 0, s[52:53]
	v_sub_f32_e32 v75, v75, v43
	v_sub_f32_e32 v74, v74, v42
	v_sub_f32_e32 v77, v77, v41
	v_sub_f32_e32 v76, v76, v40
	v_lshlrev_b32_e32 v68, 16, v64
	v_and_b32_e32 v64, 0xffff0000, v64
	v_lshlrev_b32_e32 v69, 16, v65
	v_and_b32_e32 v65, 0xffff0000, v65
	v_cndmask_b32_e64 v73, v64, 0, s[52:53]
	v_cndmask_b32_e64 v71, v65, 0, s[52:53]
	ds_read_b128 v[62:65], v59 offset:17408
	v_cndmask_b32_e64 v72, v68, 0, s[52:53]
	v_cndmask_b32_e64 v70, v69, 0, s[52:53]
	v_cndmask_b32_e64 v68, v66, 0, s[52:53]
	v_cndmask_b32_e64 v69, v67, 0, s[52:53]
	v_sub_f32_e32 v67, v61, v49
	v_sub_f32_e32 v66, v11, v48
	v_sub_f32_e32 v69, v69, v51
	v_sub_f32_e32 v68, v68, v50
	s_waitcnt lgkmcnt(0)
	v_pk_fma_f32 v[68:69], v[64:65], v[68:69], v[50:51]
	v_pk_fma_f32 v[66:67], v[62:63], v[66:67], v[48:49]
	ds_read_b128 v[62:65], v59 offset:21504
	v_sub_f32_e32 v71, v71, v47
	v_sub_f32_e32 v70, v70, v46
	v_sub_f32_e32 v73, v73, v45
	v_sub_f32_e32 v72, v72, v44
	s_waitcnt lgkmcnt(0)
	v_pk_fma_f32 v[72:73], v[62:63], v[72:73], v[44:45]
	v_pk_fma_f32 v[70:71], v[64:65], v[70:71], v[46:47]
	ds_read_b128 v[62:65], v59 offset:25600
	s_waitcnt lgkmcnt(0)
	v_pk_fma_f32 v[64:65], v[64:65], v[74:75], v[42:43]
	v_add_co_u32_e32 v74, vcc, s97, v52
	v_pk_fma_f32 v[62:63], v[62:63], v[76:77], v[40:41]
	s_nop 0
	v_addc_co_u32_e32 v75, vcc, 0, v53, vcc
	s_waitcnt vmcnt(41)
	v_mov_b32_e32 v74, v152
	v_mov_b32_e32 v75, v153
	v_lshlrev_b32_e32 v76, 16, v74
	v_and_b32_e32 v77, 0xffff0000, v74
	v_lshlrev_b32_e32 v74, 16, v75
	v_and_b32_e32 v75, 0xffff0000, v75
	v_pk_add_f32 v[74:75], v[74:75], -1.0 op_sel_hi:[1,0]
	v_pk_add_f32 v[76:77], v[76:77], -1.0 op_sel_hi:[1,0]
	v_pk_fma_f32 v[74:75], v[6:7], v[74:75], 1.0 op_sel_hi:[1,1,0]
	v_pk_fma_f32 v[76:77], v[4:5], v[76:77], 1.0 op_sel_hi:[1,1,0]
	v_pk_mul_f32 v[70:71], v[70:71], v[74:75]
	v_pk_mul_f32 v[72:73], v[72:73], v[76:77]
	v_pk_mul_f32 v[68:69], v[68:69], v[70:71]
	v_pk_mul_f32 v[66:67], v[66:67], v[72:73]
	v_pk_mul_f32 v[68:69], v[2:3], v[68:69]
	v_pk_mul_f32 v[66:67], v[0:1], v[66:67]
	s_nop 0
	v_pk_mov_b32 v[70:71], v[66:67], v[68:69] op_sel:[1,0]
	v_mov_b32_e32 v67, v69
	v_pk_add_f32 v[66:67], v[70:71], v[66:67]
	s_nop 0
	v_add_f32_e32 v11, v66, v67
	s_nop 1
	v_add_f32_dpp v11, v11, v11 quad_perm:[1,0,3,2] row_mask:0xf bank_mask:0xf bound_ctrl:1
	s_nop 1
	v_add_f32_dpp v11, v11, v11 quad_perm:[2,3,0,1] row_mask:0xf bank_mask:0xf bound_ctrl:1
	s_nop 1
	v_add_f32_dpp v11, v11, v11 row_half_mirror row_mask:0xf bank_mask:0xf bound_ctrl:1
	s_nop 1
	v_add_f32_dpp v66, v11, v11 row_mirror row_mask:0xf bank_mask:0xf bound_ctrl:1
	v_pk_fma_f32 v[62:63], v[62:63], v[66:67], v[54:55] op_sel_hi:[1,0,1]
	v_lshl_add_u64 v[54:55], s[56:57], 0, v[32:33]
	v_pk_fma_f32 v[64:65], v[64:65], v[66:67], v[56:57] op_sel_hi:[1,0,1]
	v_add_co_u32_e32 v56, vcc, s11, v54
	v_lshl_add_u64 v[32:33], v[32:33], 0, s[48:49]
	s_nop 0
	v_addc_co_u32_e32 v57, vcc, 0, v55, vcc
	v_add_co_u32_e32 v54, vcc, s13, v54
	s_waitcnt vmcnt(40)
	v_mov_b32_e32 v66, v154
	v_mov_b32_e32 v67, v155
	s_nop 0
	v_addc_co_u32_e32 v55, vcc, 0, v55, vcc
	s_waitcnt vmcnt(39)
	v_mov_b32_e32 v54, v156
	v_mov_b32_e32 v55, v157
	v_lshlrev_b32_e32 v11, 16, v66
	s_waitcnt vmcnt(38)
	v_mov_b32_e32 v56, v158
	v_mov_b32_e32 v57, v159
	v_and_b32_e32 v61, 0xffff0000, v66
	v_lshlrev_b32_e32 v70, 16, v54
	v_and_b32_e32 v54, 0xffff0000, v54
	v_lshlrev_b32_e32 v71, 16, v55
	v_and_b32_e32 v55, 0xffff0000, v55
	v_cndmask_b32_e64 v72, v55, 0, s[50:51]
	v_cndmask_b32_e64 v73, v54, 0, s[50:51]
	v_lshlrev_b32_e32 v66, 16, v67
	v_and_b32_e32 v67, 0xffff0000, v67
	v_cndmask_b32_e64 v11, v11, 0, s[50:51]
	v_cndmask_b32_e64 v61, v61, 0, s[50:51]
	v_cndmask_b32_e64 v70, v70, 0, s[50:51]
	v_cndmask_b32_e64 v71, v71, 0, s[50:51]
	v_lshlrev_b32_e32 v68, 16, v56
	v_and_b32_e32 v56, 0xffff0000, v56
	v_lshlrev_b32_e32 v69, 16, v57
	v_and_b32_e32 v57, 0xffff0000, v57
	v_cndmask_b32_e64 v75, v56, 0, s[50:51]
	v_cndmask_b32_e64 v77, v57, 0, s[50:51]
	ds_read_b128 v[54:57], v59 offset:29696
	v_cndmask_b32_e64 v74, v68, 0, s[50:51]
	v_cndmask_b32_e64 v76, v69, 0, s[50:51]
	v_cndmask_b32_e64 v68, v66, 0, s[50:51]
	v_cndmask_b32_e64 v69, v67, 0, s[50:51]
	v_sub_f32_e32 v67, v61, v49
	v_sub_f32_e32 v66, v11, v48
	v_sub_f32_e32 v69, v69, v51
	v_sub_f32_e32 v68, v68, v50
	s_waitcnt lgkmcnt(0)
	v_pk_fma_f32 v[56:57], v[56:57], v[68:69], v[50:51]
	v_pk_fma_f32 v[54:55], v[54:55], v[66:67], v[48:49]
	ds_read_b128 v[48:51], v59 offset:33792
	v_sub_f32_e32 v67, v77, v47
	v_sub_f32_e32 v66, v76, v46
	v_sub_f32_e32 v69, v75, v45
	v_sub_f32_e32 v68, v74, v44
	s_waitcnt lgkmcnt(0)
	v_pk_fma_f32 v[48:49], v[48:49], v[68:69], v[44:45]
	v_pk_fma_f32 v[50:51], v[50:51], v[66:67], v[46:47]
	ds_read_b128 v[44:47], v59 offset:37888
	v_sub_f32_e32 v67, v73, v41
	v_sub_f32_e32 v66, v70, v40
	v_sub_f32_e32 v69, v72, v43
	v_sub_f32_e32 v68, v71, v42
	s_waitcnt lgkmcnt(0)
	v_pk_fma_f32 v[40:41], v[44:45], v[66:67], v[40:41]
	v_add_co_u32_e32 v44, vcc, s70, v52
	v_pk_fma_f32 v[42:43], v[46:47], v[68:69], v[42:43]
	s_nop 0
	v_addc_co_u32_e32 v45, vcc, 0, v53, vcc
	s_waitcnt vmcnt(37)
	v_mov_b32_e32 v44, v160
	v_mov_b32_e32 v45, v161
	v_lshl_add_u64 v[66:67], s[74:75], 0, v[24:25]
	v_lshl_add_u64 v[24:25], v[24:25], 0, s[46:47]
	v_lshlrev_b32_e32 v46, 16, v44
	v_and_b32_e32 v47, 0xffff0000, v44
	v_lshlrev_b32_e32 v44, 16, v45
	v_and_b32_e32 v45, 0xffff0000, v45
	v_pk_add_f32 v[44:45], v[44:45], -1.0 op_sel_hi:[1,0]
	v_pk_add_f32 v[46:47], v[46:47], -1.0 op_sel_hi:[1,0]
	v_pk_fma_f32 v[6:7], v[6:7], v[44:45], 1.0 op_sel_hi:[1,1,0]
	v_pk_fma_f32 v[4:5], v[4:5], v[46:47], 1.0 op_sel_hi:[1,1,0]
	v_pk_mul_f32 v[6:7], v[50:51], v[6:7]
	v_pk_mul_f32 v[4:5], v[48:49], v[4:5]
	v_pk_mul_f32 v[6:7], v[56:57], v[6:7]
	v_pk_mul_f32 v[4:5], v[54:55], v[4:5]
	v_pk_mul_f32 v[2:3], v[2:3], v[6:7]
	v_pk_mul_f32 v[0:1], v[0:1], v[4:5]
	v_lshl_add_u64 v[46:47], s[54:55], 0, v[30:31]
	v_pk_mov_b32 v[4:5], v[0:1], v[2:3] op_sel:[1,0]
	v_mov_b32_e32 v1, v3
	s_waitcnt vmcnt(36)
	v_mov_b32_e32 v2, v162
	v_mov_b32_e32 v3, v163
	v_pk_add_f32 v[0:1], v[4:5], v[0:1]
	v_lshlrev_b32_e32 v6, 16, v2
	v_add_f32_e32 v0, v0, v1
	v_and_b32_e32 v7, 0xffff0000, v2
	v_lshlrev_b32_e32 v2, 16, v3
	v_add_f32_dpp v0, v0, v0 quad_perm:[1,0,3,2] row_mask:0xf bank_mask:0xf bound_ctrl:1
	v_and_b32_e32 v3, 0xffff0000, v3
	s_nop 0
	v_add_f32_dpp v0, v0, v0 quad_perm:[2,3,0,1] row_mask:0xf bank_mask:0xf bound_ctrl:1
	s_nop 1
	v_add_f32_dpp v0, v0, v0 row_half_mirror row_mask:0xf bank_mask:0xf bound_ctrl:1
	s_nop 1
	v_add_f32_dpp v0, v0, v0 row_mirror row_mask:0xf bank_mask:0xf bound_ctrl:1
	v_pk_fma_f32 v[4:5], v[40:41], v[0:1], v[62:63] op_sel_hi:[1,0,1]
	v_pk_fma_f32 v[0:1], v[42:43], v[0:1], v[64:65] op_sel_hi:[1,0,1]
	s_nop 0
	v_pk_mul_f32 v[2:3], v[0:1], v[2:3]
	v_pk_mul_f32 v[0:1], v[4:5], v[6:7]
	ds_write_b128 v60, v[0:3] offset:1024
	v_pk_mul_f32 v[2:3], v[2:3], v[2:3]
	v_pk_mul_f32 v[0:1], v[0:1], v[0:1]
	s_nop 0
	v_pk_mov_b32 v[4:5], v[0:1], v[2:3] op_sel:[1,0]
	v_mov_b32_e32 v1, v3
	v_pk_add_f32 v[0:1], v[4:5], v[0:1]
	s_nop 0
	v_pk_add_f32 v[40:41], v[0:1], v[0:1] op_sel:[0,1] op_sel_hi:[1,0]
	s_waitcnt vmcnt(29)
	v_mov_b32_e32 v0, v164
	v_mov_b32_e32 v1, v165
	v_mov_b32_e32 v2, v166
	v_mov_b32_e32 v3, v167
	global_load_dwordx4 v[100:103], v89, s[74:75]
	s_waitcnt vmcnt(29)
	v_mov_b32_e32 v4, v168
	v_mov_b32_e32 v5, v169
	v_mov_b32_e32 v6, v170
	v_mov_b32_e32 v7, v171
	global_load_dwordx4 v[104:107], v90, s[74:75]
	v_pk_add_f32 v[2:3], v[2:3], v[6:7]
	v_pk_add_f32 v[0:1], v[0:1], v[4:5]
	v_mov_b32_e32 v7, v3
	v_pk_mov_b32 v[4:5], v[0:1], v[2:3] op_sel:[1,0]
	v_mov_b32_e32 v6, v0
	v_pk_add_f32 v[4:5], v[4:5], v[6:7]
	s_nop 0
	v_add_f32_e32 v4, v4, v5
	s_nop 1
	v_add_f32_dpp v4, v4, v4 quad_perm:[1,0,3,2] row_mask:0xf bank_mask:0xf bound_ctrl:1
	s_nop 1
	v_add_f32_dpp v4, v4, v4 quad_perm:[2,3,0,1] row_mask:0xf bank_mask:0xf bound_ctrl:1
	s_nop 1
	v_add_f32_dpp v4, v4, v4 row_half_mirror row_mask:0xf bank_mask:0xf bound_ctrl:1
	s_nop 1
	v_add_f32_dpp v4, v4, v4 row_mirror row_mask:0xf bank_mask:0xf bound_ctrl:1
	v_fmamk_f32 v1, v4, 0xbc800000, v1
	v_fmac_f32_e32 v0, 0xbc800000, v4
	v_fmamk_f32 v3, v4, 0xbc800000, v3
	v_fmac_f32_e32 v2, 0xbc800000, v4
	v_pk_mul_f32 v[4:5], v[2:3], v[2:3]
	v_pk_mul_f32 v[6:7], v[0:1], v[0:1]
	s_nop 0
	v_pk_mov_b32 v[42:43], v[6:7], v[4:5] op_sel:[1,0]
	v_mov_b32_e32 v7, v5
	v_pk_add_f32 v[4:5], v[42:43], v[6:7]
	s_nop 0
	v_add_f32_e32 v4, v4, v5
	s_nop 1
	v_add_f32_dpp v4, v4, v4 quad_perm:[1,0,3,2] row_mask:0xf bank_mask:0xf bound_ctrl:1
	s_nop 1
	v_add_f32_dpp v4, v4, v4 quad_perm:[2,3,0,1] row_mask:0xf bank_mask:0xf bound_ctrl:1
	s_nop 1
	v_add_f32_dpp v4, v4, v4 row_half_mirror row_mask:0xf bank_mask:0xf bound_ctrl:1
	s_nop 1
	v_add_f32_dpp v4, v4, v4 row_mirror row_mask:0xf bank_mask:0xf bound_ctrl:1
	v_fmamk_f32 v4, v4, 0x3c800000, v84
	v_rsq_f32_e32 v4, v4
	s_nop 0
	v_pk_mul_f32 v[42:43], v[2:3], v[4:5] op_sel_hi:[1,0]
	v_pk_mul_f32 v[44:45], v[0:1], v[4:5] op_sel_hi:[1,0]
	ds_read_b128 v[0:3], v59 offset:2048
	ds_read_b128 v[4:7], v59 offset:6144
	s_waitcnt lgkmcnt(0)
	v_pk_fma_f32 v[0:1], v[0:1], v[44:45], v[4:5]
	v_lshl_add_u64 v[4:5], s[74:75], 0, v[30:31]
	v_pk_fma_f32 v[2:3], v[2:3], v[42:43], v[6:7]
	v_add_co_u32_e32 v6, vcc, s11, v4
	s_nop 1
	v_addc_co_u32_e32 v7, vcc, 0, v5, vcc
	v_add_co_u32_e32 v4, vcc, s13, v4
	s_waitcnt vmcnt(29)
	v_mov_b32_e32 v42, v172
	v_mov_b32_e32 v43, v173
	global_load_dwordx2 v[108:109], v91, s[74:75]
	s_nop 0
	v_addc_co_u32_e32 v5, vcc, 0, v5, vcc
	s_waitcnt vmcnt(29)
	v_mov_b32_e32 v4, v174
	v_mov_b32_e32 v5, v175
	global_load_dwordx2 v[110:111], v92, s[74:75]
	v_add_co_u32_e32 v48, vcc, s11, v46
	s_waitcnt vmcnt(29)
	v_mov_b32_e32 v6, v176
	v_mov_b32_e32 v7, v177
	global_load_dwordx2 v[112:113], v91, s[74:75] offset:2048
	s_nop 0
	v_addc_co_u32_e32 v49, vcc, 0, v47, vcc
	v_add_co_u32_e32 v46, vcc, s13, v46
	v_lshlrev_b32_e32 v50, 16, v42
	v_addc_co_u32_e32 v47, vcc, 0, v47, vcc
	v_and_b32_e32 v51, 0xffff0000, v42
	v_lshlrev_b32_e32 v52, 16, v43
	v_and_b32_e32 v53, 0xffff0000, v43
	v_lshlrev_b32_e32 v54, 16, v6
	v_and_b32_e32 v55, 0xffff0000, v6
	v_lshlrev_b32_e32 v56, 16, v7
	v_and_b32_e32 v57, 0xffff0000, v7
	v_lshlrev_b32_e32 v62, 16, v4
	v_and_b32_e32 v63, 0xffff0000, v4
	v_lshlrev_b32_e32 v64, 16, v5
	v_and_b32_e32 v65, 0xffff0000, v5
	ds_read_b128 v[4:7], v59 offset:10240
	ds_read_b128 v[42:45], v59 offset:14336
	s_waitcnt vmcnt(29)
	v_mov_b32_e32 v68, v178
	v_mov_b32_e32 v69, v179
	global_load_dwordx2 v[114:115], v93, s[74:75]
	s_nop 0
	s_waitcnt vmcnt(29)
	v_mov_b32_e32 v46, v180
	v_mov_b32_e32 v47, v181
	global_load_dwordx2 v[116:117], v94, s[74:75]
	v_lshlrev_b32_e32 v11, 16, v68
	s_waitcnt vmcnt(29)
	v_mov_b32_e32 v48, v182
	v_mov_b32_e32 v49, v183
	global_load_dwordx2 v[118:119], v93, s[74:75] offset:2048
	v_and_b32_e32 v41, 0xffff0000, v68
	v_lshlrev_b32_e32 v61, 16, v69
	v_and_b32_e32 v68, 0xffff0000, v69
	v_lshlrev_b32_e32 v71, 16, v46
	v_and_b32_e32 v46, 0xffff0000, v46
	v_lshlrev_b32_e32 v72, 16, v47
	v_and_b32_e32 v47, 0xffff0000, v47
	v_cndmask_b32_e64 v79, v46, 0, s[52:53]
	v_cndmask_b32_e64 v77, v47, 0, s[52:53]
	v_cndmask_b32_e64 v76, v72, 0, s[52:53]
	v_cndmask_b32_e64 v61, v61, 0, s[52:53]
	v_cndmask_b32_e64 v11, v11, 0, s[52:53]
	v_cndmask_b32_e64 v41, v41, 0, s[52:53]
	v_cndmask_b32_e64 v78, v71, 0, s[52:53]
	v_sub_f32_e32 v77, v77, v65
	v_sub_f32_e32 v76, v76, v64
	v_sub_f32_e32 v79, v79, v63
	v_sub_f32_e32 v78, v78, v62
	v_lshlrev_b32_e32 v69, 16, v48
	v_and_b32_e32 v48, 0xffff0000, v48
	v_lshlrev_b32_e32 v70, 16, v49
	v_and_b32_e32 v49, 0xffff0000, v49
	v_cndmask_b32_e64 v75, v48, 0, s[52:53]
	v_cndmask_b32_e64 v73, v49, 0, s[52:53]
	ds_read_b128 v[46:49], v59 offset:18432
	v_cndmask_b32_e64 v72, v70, 0, s[52:53]
	v_cndmask_b32_e64 v70, v68, 0, s[52:53]
	v_cndmask_b32_e64 v74, v69, 0, s[52:53]
	v_sub_f32_e32 v69, v41, v51
	v_sub_f32_e32 v68, v11, v50
	v_sub_f32_e32 v71, v70, v53
	v_sub_f32_e32 v70, v61, v52
	s_waitcnt lgkmcnt(0)
	v_pk_fma_f32 v[70:71], v[48:49], v[70:71], v[52:53]
	v_pk_fma_f32 v[68:69], v[46:47], v[68:69], v[50:51]
	ds_read_b128 v[46:49], v59 offset:22528
	v_sub_f32_e32 v73, v73, v57
	v_sub_f32_e32 v72, v72, v56
	v_sub_f32_e32 v75, v75, v55
	v_sub_f32_e32 v74, v74, v54
	s_waitcnt lgkmcnt(0)
	v_pk_fma_f32 v[74:75], v[46:47], v[74:75], v[54:55]
	v_pk_fma_f32 v[72:73], v[48:49], v[72:73], v[56:57]
	ds_read_b128 v[46:49], v59 offset:26624
	s_waitcnt lgkmcnt(0)
	v_pk_fma_f32 v[48:49], v[48:49], v[76:77], v[64:65]
	v_add_co_u32_e32 v76, vcc, s97, v66
	v_pk_fma_f32 v[46:47], v[46:47], v[78:79], v[62:63]
	s_nop 0
	v_addc_co_u32_e32 v77, vcc, 0, v67, vcc
	s_waitcnt vmcnt(29)
	v_mov_b32_e32 v76, v184
	v_mov_b32_e32 v77, v185
	global_load_dwordx2 v[120:121], v97, s[74:75]
	v_lshlrev_b32_e32 v78, 16, v76
	v_and_b32_e32 v79, 0xffff0000, v76
	v_lshlrev_b32_e32 v76, 16, v77
	v_and_b32_e32 v77, 0xffff0000, v77
	v_pk_add_f32 v[76:77], v[76:77], -1.0 op_sel_hi:[1,0]
	v_pk_add_f32 v[78:79], v[78:79], -1.0 op_sel_hi:[1,0]
	v_pk_fma_f32 v[76:77], v[44:45], v[76:77], 1.0 op_sel_hi:[1,1,0]
	v_pk_fma_f32 v[78:79], v[42:43], v[78:79], 1.0 op_sel_hi:[1,1,0]
	v_pk_mul_f32 v[72:73], v[72:73], v[76:77]
	v_pk_mul_f32 v[74:75], v[74:75], v[78:79]
	v_pk_mul_f32 v[70:71], v[70:71], v[72:73]
	v_pk_mul_f32 v[68:69], v[68:69], v[74:75]
	v_pk_mul_f32 v[70:71], v[6:7], v[70:71]
	v_pk_mul_f32 v[68:69], v[4:5], v[68:69]
	s_nop 0
	v_pk_mov_b32 v[72:73], v[68:69], v[70:71] op_sel:[1,0]
	v_mov_b32_e32 v69, v71
	v_pk_add_f32 v[68:69], v[72:73], v[68:69]
	s_nop 0
	v_add_f32_e32 v11, v68, v69
	s_nop 1
	v_add_f32_dpp v11, v11, v11 quad_perm:[1,0,3,2] row_mask:0xf bank_mask:0xf bound_ctrl:1
	s_nop 1
	v_add_f32_dpp v11, v11, v11 quad_perm:[2,3,0,1] row_mask:0xf bank_mask:0xf bound_ctrl:1
	s_nop 1
	v_add_f32_dpp v11, v11, v11 row_half_mirror row_mask:0xf bank_mask:0xf bound_ctrl:1
	s_nop 1
	v_add_f32_dpp v68, v11, v11 row_mirror row_mask:0xf bank_mask:0xf bound_ctrl:1
	v_pk_fma_f32 v[46:47], v[46:47], v[68:69], v[0:1] op_sel_hi:[1,0,1]
	v_lshl_add_u64 v[0:1], s[56:57], 0, v[30:31]
	v_pk_fma_f32 v[48:49], v[48:49], v[68:69], v[2:3] op_sel_hi:[1,0,1]
	v_add_co_u32_e32 v2, vcc, s11, v0
	v_lshl_add_u64 v[30:31], v[30:31], 0, s[48:49]
	s_nop 0
	v_addc_co_u32_e32 v3, vcc, 0, v1, vcc
	v_add_co_u32_e32 v0, vcc, s13, v0
	s_waitcnt vmcnt(29)
	v_mov_b32_e32 v68, v186
	v_mov_b32_e32 v69, v187
	global_load_dwordx2 v[122:123], v95, s[74:75]
	s_nop 0
	v_addc_co_u32_e32 v1, vcc, 0, v1, vcc
	s_waitcnt vmcnt(29)
	v_mov_b32_e32 v0, v188
	v_mov_b32_e32 v1, v189
	global_load_dwordx2 v[124:125], v96, s[74:75]
	v_lshlrev_b32_e32 v11, 16, v68
	s_waitcnt vmcnt(29)
	v_mov_b32_e32 v2, v190
	v_mov_b32_e32 v3, v191
	global_load_dwordx2 v[126:127], v95, s[74:75] offset:2048
	v_and_b32_e32 v41, 0xffff0000, v68
	v_lshlrev_b32_e32 v61, 16, v69
	v_and_b32_e32 v68, 0xffff0000, v69
	v_lshlrev_b32_e32 v71, 16, v0
	v_and_b32_e32 v0, 0xffff0000, v0
	v_lshlrev_b32_e32 v72, 16, v1
	v_and_b32_e32 v1, 0xffff0000, v1
	v_cndmask_b32_e64 v73, v1, 0, s[50:51]
	v_cndmask_b32_e64 v75, v0, 0, s[50:51]
	v_cndmask_b32_e64 v61, v61, 0, s[50:51]
	v_cndmask_b32_e64 v11, v11, 0, s[50:51]
	v_cndmask_b32_e64 v41, v41, 0, s[50:51]
	v_cndmask_b32_e64 v74, v71, 0, s[50:51]
	v_cndmask_b32_e64 v72, v72, 0, s[50:51]
	v_lshlrev_b32_e32 v69, 16, v2
	v_and_b32_e32 v2, 0xffff0000, v2
	v_lshlrev_b32_e32 v70, 16, v3
	v_and_b32_e32 v3, 0xffff0000, v3
	v_cndmask_b32_e64 v77, v2, 0, s[50:51]
	v_cndmask_b32_e64 v79, v3, 0, s[50:51]
	ds_read_b128 v[0:3], v59 offset:30720
	v_cndmask_b32_e64 v78, v70, 0, s[50:51]
	v_cndmask_b32_e64 v70, v68, 0, s[50:51]
	v_cndmask_b32_e64 v76, v69, 0, s[50:51]
	v_sub_f32_e32 v69, v41, v51
	v_sub_f32_e32 v68, v11, v50
	v_sub_f32_e32 v71, v70, v53
	v_sub_f32_e32 v70, v61, v52
	s_waitcnt lgkmcnt(0)
	v_pk_fma_f32 v[52:53], v[2:3], v[70:71], v[52:53]
	v_pk_fma_f32 v[50:51], v[0:1], v[68:69], v[50:51]
	ds_read_b128 v[0:3], v59 offset:34816
	v_sub_f32_e32 v69, v79, v57
	v_sub_f32_e32 v68, v78, v56
	v_sub_f32_e32 v71, v77, v55
	v_sub_f32_e32 v70, v76, v54
	s_waitcnt lgkmcnt(0)
	v_pk_fma_f32 v[54:55], v[0:1], v[70:71], v[54:55]
	v_pk_fma_f32 v[56:57], v[2:3], v[68:69], v[56:57]
	ds_read_b128 v[0:3], v59 offset:38912
	v_sub_f32_e32 v69, v75, v63
	v_sub_f32_e32 v68, v74, v62
	v_sub_f32_e32 v71, v73, v65
	v_sub_f32_e32 v70, v72, v64
	s_waitcnt lgkmcnt(0)
	v_pk_fma_f32 v[0:1], v[0:1], v[68:69], v[62:63]
	v_add_co_u32_e32 v62, vcc, s70, v66
	v_pk_fma_f32 v[2:3], v[2:3], v[70:71], v[64:65]
	s_nop 0
	v_addc_co_u32_e32 v63, vcc, 0, v67, vcc
	s_waitcnt vmcnt(29)
	v_mov_b32_e32 v62, v192
	v_mov_b32_e32 v63, v193
	global_load_dwordx2 v[128:129], v98, s[74:75]
	v_lshl_add_u64 v[70:71], s[74:75], 0, v[22:23]
	v_lshl_add_u64 v[22:23], v[22:23], 0, s[46:47]
	v_lshlrev_b32_e32 v64, 16, v62
	v_and_b32_e32 v65, 0xffff0000, v62
	v_lshlrev_b32_e32 v62, 16, v63
	v_and_b32_e32 v63, 0xffff0000, v63
	v_pk_add_f32 v[62:63], v[62:63], -1.0 op_sel_hi:[1,0]
	v_pk_add_f32 v[64:65], v[64:65], -1.0 op_sel_hi:[1,0]
	v_pk_fma_f32 v[44:45], v[44:45], v[62:63], 1.0 op_sel_hi:[1,1,0]
	v_pk_fma_f32 v[42:43], v[42:43], v[64:65], 1.0 op_sel_hi:[1,1,0]
	v_pk_mul_f32 v[44:45], v[56:57], v[44:45]
	v_pk_mul_f32 v[42:43], v[54:55], v[42:43]
	v_pk_mul_f32 v[44:45], v[52:53], v[44:45]
	v_pk_mul_f32 v[42:43], v[50:51], v[42:43]
	v_pk_mul_f32 v[6:7], v[6:7], v[44:45]
	v_pk_mul_f32 v[4:5], v[4:5], v[42:43]
	v_lshl_add_u64 v[50:51], s[54:55], 0, v[28:29]
	v_pk_mov_b32 v[42:43], v[4:5], v[6:7] op_sel:[1,0]
	v_mov_b32_e32 v5, v7
	v_pk_add_f32 v[4:5], v[42:43], v[4:5]
	s_nop 0
	v_add_f32_e32 v4, v4, v5
	s_nop 1
	v_add_f32_dpp v4, v4, v4 quad_perm:[1,0,3,2] row_mask:0xf bank_mask:0xf bound_ctrl:1
	s_nop 1
	v_add_f32_dpp v4, v4, v4 quad_perm:[2,3,0,1] row_mask:0xf bank_mask:0xf bound_ctrl:1
	s_nop 1
	v_add_f32_dpp v4, v4, v4 row_half_mirror row_mask:0xf bank_mask:0xf bound_ctrl:1
	s_nop 1
	v_add_f32_dpp v4, v4, v4 row_mirror row_mask:0xf bank_mask:0xf bound_ctrl:1
	v_pk_fma_f32 v[0:1], v[0:1], v[4:5], v[46:47] op_sel_hi:[1,0,1]
	v_pk_fma_f32 v[2:3], v[2:3], v[4:5], v[48:49] op_sel_hi:[1,0,1]
	s_waitcnt vmcnt(29)
	v_mov_b32_e32 v4, v194
	v_mov_b32_e32 v5, v195
	global_load_dwordx2 v[130:131], v99, s[74:75]
	v_lshlrev_b32_e32 v6, 16, v4
	v_and_b32_e32 v7, 0xffff0000, v4
	v_lshlrev_b32_e32 v4, 16, v5
	v_and_b32_e32 v5, 0xffff0000, v5
	v_pk_mul_f32 v[2:3], v[2:3], v[4:5]
	v_pk_mul_f32 v[0:1], v[0:1], v[6:7]
	ds_write_b128 v60, v[0:3] offset:2048
	v_pk_mul_f32 v[4:5], v[2:3], v[2:3]
	v_pk_mul_f32 v[6:7], v[0:1], v[0:1]
	v_add_f32_e32 v44, v4, v5
	v_add_f32_e32 v42, v6, v7
	s_waitcnt vmcnt(29)
	v_mov_b32_e32 v4, v196
	v_mov_b32_e32 v5, v197
	v_mov_b32_e32 v6, v198
	v_mov_b32_e32 v7, v199
	global_load_dwordx4 v[132:135], v89, s[74:75] offset:1024
	s_nop 0
	s_waitcnt vmcnt(29)
	v_mov_b32_e32 v36, v200
	v_mov_b32_e32 v37, v201
	v_mov_b32_e32 v38, v202
	v_mov_b32_e32 v39, v203
	global_load_dwordx4 v[136:139], v90, s[74:75] offset:1024
	v_pk_add_f32 v[6:7], v[6:7], v[38:39]
	v_pk_add_f32 v[4:5], v[4:5], v[36:37]
	v_mov_b32_e32 v39, v7
	v_pk_mov_b32 v[36:37], v[4:5], v[6:7] op_sel:[1,0]
	v_mov_b32_e32 v38, v4
	v_pk_add_f32 v[36:37], v[36:37], v[38:39]
	s_nop 0
	v_add_f32_e32 v11, v36, v37
	s_nop 1
	v_add_f32_dpp v11, v11, v11 quad_perm:[1,0,3,2] row_mask:0xf bank_mask:0xf bound_ctrl:1
	s_nop 1
	v_add_f32_dpp v11, v11, v11 quad_perm:[2,3,0,1] row_mask:0xf bank_mask:0xf bound_ctrl:1
	s_nop 1
	v_add_f32_dpp v11, v11, v11 row_half_mirror row_mask:0xf bank_mask:0xf bound_ctrl:1
	s_nop 1
	v_add_f32_dpp v11, v11, v11 row_mirror row_mask:0xf bank_mask:0xf bound_ctrl:1
	v_fmamk_f32 v5, v11, 0xbc800000, v5
	v_fmac_f32_e32 v4, 0xbc800000, v11
	v_fmamk_f32 v7, v11, 0xbc800000, v7
	v_fmac_f32_e32 v6, 0xbc800000, v11
	v_pk_mul_f32 v[36:37], v[6:7], v[6:7]
	v_pk_mul_f32 v[38:39], v[4:5], v[4:5]
	s_nop 0
	v_pk_mov_b32 v[46:47], v[38:39], v[36:37] op_sel:[1,0]
	v_mov_b32_e32 v39, v37
	v_pk_add_f32 v[36:37], v[46:47], v[38:39]
	s_nop 0
	v_add_f32_e32 v11, v36, v37
	s_nop 1
	v_add_f32_dpp v11, v11, v11 quad_perm:[1,0,3,2] row_mask:0xf bank_mask:0xf bound_ctrl:1
	s_nop 1
	v_add_f32_dpp v11, v11, v11 quad_perm:[2,3,0,1] row_mask:0xf bank_mask:0xf bound_ctrl:1
	s_nop 1
	v_add_f32_dpp v11, v11, v11 row_half_mirror row_mask:0xf bank_mask:0xf bound_ctrl:1
	s_nop 1
	v_add_f32_dpp v11, v11, v11 row_mirror row_mask:0xf bank_mask:0xf bound_ctrl:1
	v_fmamk_f32 v11, v11, 0x3c800000, v84
	v_rsq_f32_e32 v36, v11
	s_nop 0
	v_pk_mul_f32 v[46:47], v[6:7], v[36:37] op_sel_hi:[1,0]
	v_pk_mul_f32 v[48:49], v[4:5], v[36:37] op_sel_hi:[1,0]
	ds_read_b128 v[4:7], v59 offset:3072
	ds_read_b128 v[36:39], v59 offset:7168
	s_waitcnt lgkmcnt(0)
	v_pk_fma_f32 v[4:5], v[4:5], v[48:49], v[36:37]
	v_lshl_add_u64 v[36:37], s[74:75], 0, v[28:29]
	v_pk_fma_f32 v[6:7], v[6:7], v[46:47], v[38:39]
	v_add_co_u32_e32 v38, vcc, s11, v36
	s_nop 1
	v_addc_co_u32_e32 v39, vcc, 0, v37, vcc
	v_add_co_u32_e32 v36, vcc, s13, v36
	s_waitcnt vmcnt(29)
	v_mov_b32_e32 v46, v204
	v_mov_b32_e32 v47, v205
	global_load_dwordx2 v[140:141], v91, s[74:75] offset:512
	s_nop 0
	v_addc_co_u32_e32 v37, vcc, 0, v37, vcc
	s_waitcnt vmcnt(29)
	v_mov_b32_e32 v36, v206
	v_mov_b32_e32 v37, v207
	global_load_dwordx2 v[142:143], v92, s[74:75] offset:512
	v_add_co_u32_e32 v52, vcc, s11, v50
	s_waitcnt vmcnt(29)
	v_mov_b32_e32 v38, v210
	v_mov_b32_e32 v39, v211
	global_load_dwordx2 v[144:145], v91, s[74:75] offset:2560
	s_nop 0
	v_addc_co_u32_e32 v53, vcc, 0, v51, vcc
	v_add_co_u32_e32 v50, vcc, s13, v50
	v_lshlrev_b32_e32 v54, 16, v46
	v_addc_co_u32_e32 v51, vcc, 0, v51, vcc
	v_and_b32_e32 v55, 0xffff0000, v46
	v_lshlrev_b32_e32 v56, 16, v47
	v_and_b32_e32 v57, 0xffff0000, v47
	v_lshlrev_b32_e32 v62, 16, v38
	v_and_b32_e32 v63, 0xffff0000, v38
	v_lshlrev_b32_e32 v64, 16, v39
	v_and_b32_e32 v65, 0xffff0000, v39
	v_lshlrev_b32_e32 v66, 16, v36
	v_and_b32_e32 v67, 0xffff0000, v36
	v_lshlrev_b32_e32 v68, 16, v37
	v_and_b32_e32 v69, 0xffff0000, v37
	ds_read_b128 v[36:39], v59 offset:11264
	ds_read_b128 v[46:49], v59 offset:15360
	s_waitcnt vmcnt(29)
	v_mov_b32_e32 v72, v212
	v_mov_b32_e32 v73, v213
	global_load_dwordx2 v[146:147], v93, s[74:75] offset:512
	s_nop 0
	s_waitcnt vmcnt(29)
	v_mov_b32_e32 v50, v214
	v_mov_b32_e32 v51, v215
	global_load_dwordx2 v[148:149], v94, s[74:75] offset:512
	v_lshlrev_b32_e32 v11, 16, v72
	s_waitcnt vmcnt(29)
	v_mov_b32_e32 v52, v216
	v_mov_b32_e32 v53, v217
	global_load_dwordx2 v[150:151], v93, s[74:75] offset:2560
	v_and_b32_e32 v41, 0xffff0000, v72
	v_lshlrev_b32_e32 v43, 16, v73
	v_and_b32_e32 v45, 0xffff0000, v73
	v_lshlrev_b32_e32 v73, 16, v50
	v_and_b32_e32 v50, 0xffff0000, v50
	v_lshlrev_b32_e32 v74, 16, v51
	v_and_b32_e32 v51, 0xffff0000, v51
	v_cndmask_b32_e64 v83, v50, 0, s[52:53]
	v_cndmask_b32_e64 v81, v51, 0, s[52:53]
	v_cndmask_b32_e64 v43, v43, 0, s[52:53]
	v_cndmask_b32_e64 v45, v45, 0, s[52:53]
	v_cndmask_b32_e64 v11, v11, 0, s[52:53]
	v_cndmask_b32_e64 v41, v41, 0, s[52:53]
	v_cndmask_b32_e64 v82, v73, 0, s[52:53]
	v_cndmask_b32_e64 v80, v74, 0, s[52:53]
	v_sub_f32_e32 v73, v41, v55
	v_sub_f32_e32 v75, v45, v57
	v_sub_f32_e32 v74, v43, v56
	v_sub_f32_e32 v81, v81, v69
	v_sub_f32_e32 v80, v80, v68
	v_sub_f32_e32 v83, v83, v67
	v_sub_f32_e32 v82, v82, v66
	s_waitcnt vmcnt(29)
	v_mov_b32_e32 v8, v218
	v_mov_b32_e32 v9, v219
	global_load_dwordx2 v[152:153], v97, s[74:75] offset:512
	v_lshlrev_b32_e32 v61, 16, v52
	v_and_b32_e32 v52, 0xffff0000, v52
	v_lshlrev_b32_e32 v72, 16, v53
	v_and_b32_e32 v53, 0xffff0000, v53
	v_cndmask_b32_e64 v78, v52, 0, s[52:53]
	v_cndmask_b32_e64 v77, v53, 0, s[52:53]
	ds_read_b128 v[50:53], v59 offset:19456
	v_cndmask_b32_e64 v76, v72, 0, s[52:53]
	v_sub_f32_e32 v72, v11, v54
	v_cndmask_b32_e64 v61, v61, 0, s[52:53]
	v_sub_f32_e32 v77, v77, v65
	s_waitcnt lgkmcnt(0)
	v_pk_fma_f32 v[74:75], v[52:53], v[74:75], v[56:57]
	v_pk_fma_f32 v[72:73], v[50:51], v[72:73], v[54:55]
	ds_read_b128 v[50:53], v59 offset:23552
	v_sub_f32_e32 v76, v76, v64
	v_sub_f32_e32 v79, v78, v63
	v_sub_f32_e32 v78, v61, v62
	s_waitcnt lgkmcnt(0)
	v_pk_fma_f32 v[78:79], v[50:51], v[78:79], v[62:63]
	v_pk_fma_f32 v[76:77], v[52:53], v[76:77], v[64:65]
	ds_read_b128 v[50:53], v59 offset:27648
	s_waitcnt lgkmcnt(0)
	v_pk_fma_f32 v[52:53], v[52:53], v[80:81], v[68:69]
	v_add_co_u32_e32 v80, vcc, s97, v70
	v_pk_fma_f32 v[50:51], v[50:51], v[82:83], v[66:67]
	s_nop 0
	v_addc_co_u32_e32 v81, vcc, 0, v71, vcc
	s_waitcnt vmcnt(29)
	v_mov_b32_e32 v80, v220
	v_mov_b32_e32 v81, v221
	global_load_dwordx2 v[154:155], v95, s[74:75] offset:512
	v_lshlrev_b32_e32 v82, 16, v80
	v_and_b32_e32 v83, 0xffff0000, v80
	v_lshlrev_b32_e32 v80, 16, v81
	v_and_b32_e32 v81, 0xffff0000, v81
	v_pk_add_f32 v[80:81], v[80:81], -1.0 op_sel_hi:[1,0]
	v_pk_add_f32 v[82:83], v[82:83], -1.0 op_sel_hi:[1,0]
	v_pk_fma_f32 v[80:81], v[48:49], v[80:81], 1.0 op_sel_hi:[1,1,0]
	v_pk_fma_f32 v[82:83], v[46:47], v[82:83], 1.0 op_sel_hi:[1,1,0]
	v_pk_mul_f32 v[76:77], v[76:77], v[80:81]
	v_pk_mul_f32 v[78:79], v[78:79], v[82:83]
	v_pk_mul_f32 v[74:75], v[74:75], v[76:77]
	v_pk_mul_f32 v[72:73], v[72:73], v[78:79]
	v_pk_mul_f32 v[74:75], v[38:39], v[74:75]
	v_pk_mul_f32 v[72:73], v[36:37], v[72:73]
	s_nop 0
	v_pk_mov_b32 v[76:77], v[72:73], v[74:75] op_sel:[1,0]
	v_mov_b32_e32 v73, v75
	v_pk_add_f32 v[72:73], v[76:77], v[72:73]
	s_nop 0
	v_add_f32_e32 v11, v72, v73
	s_nop 1
	v_add_f32_dpp v11, v11, v11 quad_perm:[1,0,3,2] row_mask:0xf bank_mask:0xf bound_ctrl:1
	s_nop 1
	v_add_f32_dpp v11, v11, v11 quad_perm:[2,3,0,1] row_mask:0xf bank_mask:0xf bound_ctrl:1
	s_nop 1
	v_add_f32_dpp v11, v11, v11 row_half_mirror row_mask:0xf bank_mask:0xf bound_ctrl:1
	s_nop 1
	v_add_f32_dpp v72, v11, v11 row_mirror row_mask:0xf bank_mask:0xf bound_ctrl:1
	v_pk_fma_f32 v[50:51], v[50:51], v[72:73], v[4:5] op_sel_hi:[1,0,1]
	v_lshl_add_u64 v[4:5], s[56:57], 0, v[28:29]
	v_pk_fma_f32 v[52:53], v[52:53], v[72:73], v[6:7] op_sel_hi:[1,0,1]
	v_add_co_u32_e32 v6, vcc, s11, v4
	v_lshl_add_u64 v[28:29], v[28:29], 0, s[48:49]
	s_nop 0
	v_addc_co_u32_e32 v7, vcc, 0, v5, vcc
	v_add_co_u32_e32 v4, vcc, s13, v4
	s_waitcnt vmcnt(29)
	v_mov_b32_e32 v72, v222
	v_mov_b32_e32 v73, v223
	global_load_dwordx2 v[156:157], v96, s[74:75] offset:512
	s_nop 0
	v_addc_co_u32_e32 v5, vcc, 0, v5, vcc
	s_waitcnt vmcnt(29)
	v_mov_b32_e32 v4, v224
	v_mov_b32_e32 v5, v225
	global_load_dwordx2 v[158:159], v95, s[74:75] offset:2560
	v_lshlrev_b32_e32 v11, 16, v72
	s_waitcnt vmcnt(29)
	v_mov_b32_e32 v6, v226
	v_mov_b32_e32 v7, v227
	global_load_dwordx2 v[160:161], v98, s[74:75] offset:512
	v_and_b32_e32 v41, 0xffff0000, v72
	v_lshlrev_b32_e32 v43, 16, v73
	v_and_b32_e32 v45, 0xffff0000, v73
	v_lshlrev_b32_e32 v73, 16, v4
	v_and_b32_e32 v4, 0xffff0000, v4
	v_lshlrev_b32_e32 v74, 16, v5
	v_and_b32_e32 v5, 0xffff0000, v5
	v_cndmask_b32_e64 v77, v5, 0, s[50:51]
	v_cndmask_b32_e64 v79, v4, 0, s[50:51]
	v_cndmask_b32_e64 v43, v43, 0, s[50:51]
	v_cndmask_b32_e64 v45, v45, 0, s[50:51]
	v_cndmask_b32_e64 v11, v11, 0, s[50:51]
	v_cndmask_b32_e64 v41, v41, 0, s[50:51]
	v_cndmask_b32_e64 v76, v74, 0, s[50:51]
	v_cndmask_b32_e64 v78, v73, 0, s[50:51]
	v_sub_f32_e32 v73, v41, v55
	v_sub_f32_e32 v75, v45, v57
	v_sub_f32_e32 v74, v43, v56
	v_lshlrev_b32_e32 v61, 16, v6
	v_and_b32_e32 v6, 0xffff0000, v6
	v_lshlrev_b32_e32 v72, 16, v7
	v_and_b32_e32 v7, 0xffff0000, v7
	v_cndmask_b32_e64 v80, v6, 0, s[50:51]
	v_cndmask_b32_e64 v82, v7, 0, s[50:51]
	ds_read_b128 v[4:7], v59 offset:31744
	v_cndmask_b32_e64 v81, v72, 0, s[50:51]
	v_sub_f32_e32 v72, v11, v54
	v_cndmask_b32_e64 v61, v61, 0, s[50:51]
	s_waitcnt lgkmcnt(0)
	v_pk_fma_f32 v[56:57], v[6:7], v[74:75], v[56:57]
	v_pk_fma_f32 v[54:55], v[4:5], v[72:73], v[54:55]
	ds_read_b128 v[4:7], v59 offset:35840
	v_sub_f32_e32 v73, v82, v65
	v_sub_f32_e32 v72, v81, v64
	v_sub_f32_e32 v75, v80, v63
	v_sub_f32_e32 v74, v61, v62
	s_waitcnt lgkmcnt(0)
	v_pk_fma_f32 v[62:63], v[4:5], v[74:75], v[62:63]
	v_pk_fma_f32 v[64:65], v[6:7], v[72:73], v[64:65]
	ds_read_b128 v[4:7], v59 offset:39936
	v_sub_f32_e32 v73, v79, v67
	v_sub_f32_e32 v72, v78, v66
	v_sub_f32_e32 v75, v77, v69
	v_sub_f32_e32 v74, v76, v68
	s_waitcnt lgkmcnt(0)
	v_pk_fma_f32 v[4:5], v[4:5], v[72:73], v[66:67]
	v_add_co_u32_e32 v66, vcc, s70, v70
	v_pk_fma_f32 v[6:7], v[6:7], v[74:75], v[68:69]
	s_nop 0
	v_addc_co_u32_e32 v67, vcc, 0, v71, vcc
	s_waitcnt vmcnt(29)
	v_mov_b32_e32 v66, v228
	v_mov_b32_e32 v67, v229
	global_load_dwordx2 v[162:163], v99, s[74:75] offset:512
	v_lshlrev_b32_e32 v68, 16, v66
	v_and_b32_e32 v69, 0xffff0000, v66
	v_lshlrev_b32_e32 v66, 16, v67
	v_and_b32_e32 v67, 0xffff0000, v67
	v_pk_add_f32 v[66:67], v[66:67], -1.0 op_sel_hi:[1,0]
	v_pk_add_f32 v[68:69], v[68:69], -1.0 op_sel_hi:[1,0]
	v_pk_fma_f32 v[48:49], v[48:49], v[66:67], 1.0 op_sel_hi:[1,1,0]
	v_pk_fma_f32 v[46:47], v[46:47], v[68:69], 1.0 op_sel_hi:[1,1,0]
	v_pk_mul_f32 v[48:49], v[64:65], v[48:49]
	v_pk_mul_f32 v[46:47], v[62:63], v[46:47]
	v_pk_mul_f32 v[48:49], v[56:57], v[48:49]
	v_pk_mul_f32 v[46:47], v[54:55], v[46:47]
	v_pk_mul_f32 v[38:39], v[38:39], v[48:49]
	v_pk_mul_f32 v[36:37], v[36:37], v[46:47]
	s_nop 0
	v_pk_mov_b32 v[46:47], v[36:37], v[38:39] op_sel:[1,0]
	v_mov_b32_e32 v37, v39
	v_pk_add_f32 v[36:37], v[46:47], v[36:37]
	v_lshl_add_u64 v[38:39], s[74:75], 0, v[16:17]
	v_add_f32_e32 v11, v36, v37
	v_lshl_add_u64 v[16:17], v[16:17], 0, s[44:45]
	s_nop 0
	v_add_f32_dpp v11, v11, v11 quad_perm:[1,0,3,2] row_mask:0xf bank_mask:0xf bound_ctrl:1
	s_nop 1
	v_add_f32_dpp v11, v11, v11 quad_perm:[2,3,0,1] row_mask:0xf bank_mask:0xf bound_ctrl:1
	s_nop 1
	v_add_f32_dpp v11, v11, v11 row_half_mirror row_mask:0xf bank_mask:0xf bound_ctrl:1
	s_nop 1
	v_add_f32_dpp v36, v11, v11 row_mirror row_mask:0xf bank_mask:0xf bound_ctrl:1
	v_pk_fma_f32 v[4:5], v[4:5], v[36:37], v[50:51] op_sel_hi:[1,0,1]
	v_pk_fma_f32 v[6:7], v[6:7], v[36:37], v[52:53] op_sel_hi:[1,0,1]
	v_lshlrev_b32_e32 v36, 16, v8
	v_and_b32_e32 v37, 0xffff0000, v8
	v_lshlrev_b32_e32 v8, 16, v9
	v_and_b32_e32 v9, 0xffff0000, v9
	v_pk_mul_f32 v[6:7], v[6:7], v[8:9]
	v_pk_mul_f32 v[4:5], v[4:5], v[36:37]
	v_pk_mul_f32 v[8:9], v[6:7], v[6:7]
	v_pk_mul_f32 v[36:37], v[4:5], v[4:5]
	v_mov_b32_e32 v43, v8
	v_mov_b32_e32 v11, v36
	v_mov_b32_e32 v41, v37
	v_mov_b32_e32 v45, v9
	v_pk_add_f32 v[10:11], v[10:11], v[40:41]
	v_pk_add_f32 v[8:9], v[42:43], v[44:45]
	ds_write_b128 v60, v[4:7] offset:3072
	v_pk_add_f32 v[8:9], v[10:11], v[8:9]
	s_nop 0
	v_add_f32_e32 v8, v8, v9
	s_nop 1
	v_add_f32_dpp v8, v8, v8 quad_perm:[1,0,3,2] row_mask:0xf bank_mask:0xf bound_ctrl:1
	s_nop 1
	v_add_f32_dpp v8, v8, v8 quad_perm:[2,3,0,1] row_mask:0xf bank_mask:0xf bound_ctrl:1
	s_nop 1
	v_add_f32_dpp v8, v8, v8 row_half_mirror row_mask:0xf bank_mask:0xf bound_ctrl:1
	s_nop 1
	v_add_f32_dpp v8, v8, v8 row_mirror row_mask:0xf bank_mask:0xf bound_ctrl:1
	s_nop 0
	v_readlane_b32 s2, v8, 16
	v_readlane_b32 s6, v8, 48
	v_readlane_b32 s4, v8, 0
	v_readlane_b32 s5, v8, 32
	v_mov_b32_e32 v8, s2
	v_mov_b32_e32 v9, s6
	v_pk_add_f32 v[8:9], s[4:5], v[8:9]
	s_mov_b32 s2, 0x2fe00000
	v_add_f32_e32 v8, v8, v9
	v_fmamk_f32 v8, v8, 0x3a800000, v252
	v_rsq_f32_e32 v36, v8
	v_add_co_u32_e32 v8, vcc, s12, v38
	s_nop 1
	v_addc_co_u32_e32 v9, vcc, 0, v39, vcc
	v_add_co_u32_e32 v38, vcc, s2, v38
	s_nop 1
	v_addc_co_u32_e32 v39, vcc, 0, v39, vcc
	s_waitcnt vmcnt(29)
	v_mov_b32_e32 v8, v232
	v_mov_b32_e32 v9, v233
	v_mov_b32_e32 v10, v234
	v_mov_b32_e32 v11, v235
	v_lshlrev_b32_e32 v48, 16, v8
	v_and_b32_e32 v49, 0xffff0000, v8
	v_lshlrev_b32_e32 v52, 16, v10
	v_and_b32_e32 v53, 0xffff0000, v10
	v_lshlrev_b32_e32 v8, 16, v9
	v_and_b32_e32 v9, 0xffff0000, v9
	v_lshlrev_b32_e32 v54, 16, v11
	v_and_b32_e32 v55, 0xffff0000, v11
	v_pk_mul_f32 v[46:47], v[48:49], v[48:49]
	v_pk_mul_f32 v[56:57], v[52:53], v[52:53]
	v_pk_mul_f32 v[10:11], v[8:9], v[8:9]
	v_pk_mul_f32 v[50:51], v[54:55], v[54:55]
	v_mov_b32_e32 v62, v46
	v_mov_b32_e32 v63, v56
	v_mov_b32_e32 v56, v47
	v_pk_add_f32 v[46:47], v[62:63], v[56:57]
	v_mov_b32_e32 v56, v10
	v_mov_b32_e32 v57, v50
	v_mov_b32_e32 v50, v11
	v_pk_add_f32 v[10:11], v[56:57], v[50:51]
	s_waitcnt vmcnt(28)
	v_mov_b32_e32 v38, v240
	v_mov_b32_e32 v39, v241
	v_mov_b32_e32 v40, v242
	v_mov_b32_e32 v41, v243
	v_lshlrev_b32_e32 v42, 16, v38
	v_pk_add_f32 v[10:11], v[46:47], v[10:11]
	v_and_b32_e32 v43, 0xffff0000, v38
	v_add_f32_e32 v10, v10, v11
	v_lshlrev_b32_e32 v44, 16, v39
	v_and_b32_e32 v45, 0xffff0000, v39
	v_add_f32_dpp v10, v10, v10 quad_perm:[1,0,3,2] row_mask:0xf bank_mask:0xf bound_ctrl:1
	v_lshlrev_b32_e32 v38, 16, v40
	v_and_b32_e32 v39, 0xffff0000, v40
	v_add_f32_dpp v10, v10, v10 quad_perm:[2,3,0,1] row_mask:0xf bank_mask:0xf bound_ctrl:1
	v_lshlrev_b32_e32 v40, 16, v41
	v_and_b32_e32 v41, 0xffff0000, v41
	v_add_f32_dpp v10, v10, v10 row_half_mirror row_mask:0xf bank_mask:0xf bound_ctrl:1
	v_pk_mul_f32 v[46:47], v[42:43], v[42:43]
	v_pk_mul_f32 v[62:63], v[38:39], v[38:39]
	v_add_f32_dpp v10, v10, v10 row_mirror row_mask:0xf bank_mask:0xf bound_ctrl:1
	v_pk_mul_f32 v[50:51], v[40:41], v[40:41]
	v_readlane_b32 s2, v10, 16
	v_readlane_b32 s6, v10, 48
	v_readlane_b32 s4, v10, 0
	v_readlane_b32 s5, v10, 32
	v_mov_b32_e32 v10, s2
	v_mov_b32_e32 v11, s6
	v_pk_add_f32 v[10:11], s[4:5], v[10:11]
	v_mov_b32_e32 v64, v46
	v_add_f32_e32 v10, v10, v11
	v_fmamk_f32 v10, v10, 0x3b000000, v252
	v_rsq_f32_e32 v56, v10
	v_pk_mul_f32 v[10:11], v[44:45], v[44:45]
	v_mov_b32_e32 v65, v62
	v_mov_b32_e32 v62, v47
	v_pk_add_f32 v[46:47], v[64:65], v[62:63]
	v_mov_b32_e32 v62, v10
	v_mov_b32_e32 v63, v50
	v_mov_b32_e32 v50, v11
	v_pk_add_f32 v[10:11], v[62:63], v[50:51]
	v_pk_mul_f32 v[62:63], v[56:57], v[48:49] op_sel_hi:[0,1]
	v_pk_add_f32 v[10:11], v[46:47], v[10:11]
	v_pk_mul_f32 v[64:65], v[56:57], v[8:9] op_sel_hi:[0,1]
	v_add_f32_e32 v10, v10, v11
	v_pk_mul_f32 v[52:53], v[56:57], v[52:53] op_sel_hi:[0,1]
	v_pk_mul_f32 v[54:55], v[56:57], v[54:55] op_sel_hi:[0,1]
	v_add_f32_dpp v10, v10, v10 quad_perm:[1,0,3,2] row_mask:0xf bank_mask:0xf bound_ctrl:1
	s_nop 1
	v_add_f32_dpp v10, v10, v10 quad_perm:[2,3,0,1] row_mask:0xf bank_mask:0xf bound_ctrl:1
	s_nop 1
	v_add_f32_dpp v10, v10, v10 row_half_mirror row_mask:0xf bank_mask:0xf bound_ctrl:1
	s_nop 1
	v_add_f32_dpp v10, v10, v10 row_mirror row_mask:0xf bank_mask:0xf bound_ctrl:1
	s_nop 0
	v_readlane_b32 s2, v10, 16
	v_readlane_b32 s6, v10, 48
	v_readlane_b32 s4, v10, 0
	v_readlane_b32 s5, v10, 32
	v_mov_b32_e32 v10, s2
	v_mov_b32_e32 v11, s6
	v_pk_add_f32 v[10:11], s[4:5], v[10:11]
	s_nop 0
	v_add_f32_e32 v10, v10, v11
	v_fmamk_f32 v10, v10, 0x3b000000, v252
	v_rsq_f32_e32 v46, v10
	ds_read_b128 v[8:11], v58 offset:40960
	ds_read_b128 v[48:51], v58 offset:40976
	v_pk_mul_f32 v[42:43], v[46:47], v[42:43] op_sel_hi:[0,1]
	s_waitcnt lgkmcnt(1)
	v_pk_mul_f32 v[8:9], v[62:63], v[8:9]
	v_pk_mul_f32 v[10:11], v[64:65], v[10:11]
	v_bfe_u32 v37, v8, 16, 1
	v_add3_u32 v8, v8, v37, s3
	v_bfe_u32 v37, v9, 16, 1
	v_lshrrev_b32_e32 v8, 16, v8
	v_add3_u32 v9, v9, v37, s3
	v_and_or_b32 v8, v9, s29, v8
	v_bfe_u32 v9, v10, 16, 1
	v_add3_u32 v9, v10, v9, s3
	v_bfe_u32 v10, v11, 16, 1
	s_waitcnt lgkmcnt(0)
	v_pk_mul_f32 v[48:49], v[52:53], v[48:49]
	v_lshrrev_b32_e32 v9, 16, v9
	v_add3_u32 v10, v11, v10, s3
	v_and_or_b32 v9, v10, s29, v9
	v_bfe_u32 v10, v48, 16, 1
	v_add3_u32 v10, v48, v10, s3
	v_bfe_u32 v11, v49, 16, 1
	v_pk_mul_f32 v[50:51], v[54:55], v[50:51]
	v_lshrrev_b32_e32 v10, 16, v10
	v_add3_u32 v11, v49, v11, s3
	v_and_or_b32 v10, v11, s29, v10
	v_bfe_u32 v11, v50, 16, 1
	v_add3_u32 v11, v50, v11, s3
	v_bfe_u32 v37, v51, 16, 1
	v_lshl_add_u64 v[48:49], s[74:75], 0, v[14:15]
	v_lshrrev_b32_e32 v11, 16, v11
	v_add3_u32 v37, v51, v37, s3
	v_add_co_u32_e32 v48, vcc, s24, v48
	v_and_or_b32 v11, v37, s29, v11
	s_nop 0
	v_addc_co_u32_e32 v49, vcc, 0, v49, vcc
	global_store_dwordx4 v[48:49], v[8:11], off
	ds_read_b128 v[8:11], v58 offset:43008
	v_pk_mul_f32 v[44:45], v[46:47], v[44:45] op_sel_hi:[0,1]
	v_pk_mul_f32 v[38:39], v[46:47], v[38:39] op_sel_hi:[0,1]
	v_pk_mul_f32 v[40:41], v[46:47], v[40:41] op_sel_hi:[0,1]
	v_lshl_add_u64 v[14:15], v[14:15], 0, s[42:43]
	s_waitcnt lgkmcnt(0)
	v_pk_mul_f32 v[44:45], v[10:11], v[44:45]
	v_pk_mul_f32 v[42:43], v[8:9], v[42:43]
	ds_read_b128 v[8:11], v58 offset:43024
	v_bfe_u32 v37, v45, 16, 1
	v_add3_u32 v37, v45, v37, s3
	s_waitcnt lgkmcnt(0)
	v_pk_mul_f32 v[40:41], v[10:11], v[40:41]
	v_pk_mul_f32 v[10:11], v[8:9], v[38:39]
	v_bfe_u32 v8, v42, 16, 1
	v_add3_u32 v8, v42, v8, s3
	v_bfe_u32 v9, v43, 16, 1
	v_lshrrev_b32_e32 v8, 16, v8
	v_add3_u32 v9, v43, v9, s3
	v_and_or_b32 v8, v9, s29, v8
	v_bfe_u32 v9, v44, 16, 1
	v_add3_u32 v9, v44, v9, s3
	v_lshrrev_b32_e32 v9, 16, v9
	v_and_or_b32 v9, v37, s29, v9
	v_bfe_u32 v37, v10, 16, 1
	v_add3_u32 v10, v10, v37, s3
	v_bfe_u32 v37, v11, 16, 1
	v_lshrrev_b32_e32 v10, 16, v10
	v_add3_u32 v11, v11, v37, s3
	v_and_or_b32 v10, v11, s29, v10
	v_bfe_u32 v11, v40, 16, 1
	v_add3_u32 v11, v40, v11, s3
	v_bfe_u32 v37, v41, 16, 1
	v_lshrrev_b32_e32 v11, 16, v11
	v_add3_u32 v37, v41, v37, s3
	v_and_or_b32 v11, v37, s29, v11
	global_store_dwordx4 v[48:49], v[8:11], off offset:1024
	ds_read_b128 v[8:11], v60
	s_waitcnt lgkmcnt(0)
	v_pk_mul_f32 v[38:39], v[36:37], v[8:9] op_sel_hi:[0,1]
	v_pk_mul_f32 v[40:41], v[36:37], v[10:11] op_sel_hi:[0,1]
	ds_read_b128 v[8:11], v59 offset:45056
	s_waitcnt lgkmcnt(0)
	v_pk_mul_f32 v[8:9], v[38:39], v[8:9]
	s_nop 0
	v_bfe_u32 v37, v8, 16, 1
	v_add3_u32 v8, v8, v37, s3
	v_bfe_u32 v37, v9, 16, 1
	v_pk_mul_f32 v[10:11], v[40:41], v[10:11]
	v_lshrrev_b32_e32 v8, 16, v8
	v_add3_u32 v9, v9, v37, s3
	v_and_or_b32 v8, v9, s29, v8
	v_bfe_u32 v9, v10, 16, 1
	v_add3_u32 v9, v10, v9, s3
	v_bfe_u32 v10, v11, 16, 1
	v_lshrrev_b32_e32 v9, 16, v9
	v_add3_u32 v10, v11, v10, s3
	v_and_or_b32 v9, v10, s29, v9
	v_lshl_add_u64 v[10:11], s[74:75], 0, v[12:13]
	v_add_co_u32_e32 v38, vcc, s24, v10
	v_lshl_add_u64 v[12:13], v[12:13], 0, s[42:43]
	s_nop 0
	v_addc_co_u32_e32 v39, vcc, 0, v11, vcc
	global_store_dwordx2 v[38:39], v[8:9], off offset:2048
	ds_read_b128 v[8:11], v60 offset:1024
	s_waitcnt lgkmcnt(0)
	v_pk_mul_f32 v[40:41], v[36:37], v[8:9] op_sel_hi:[0,1]
	v_pk_mul_f32 v[42:43], v[36:37], v[10:11] op_sel_hi:[0,1]
	ds_read_b128 v[8:11], v59 offset:46080
	s_waitcnt lgkmcnt(0)
	v_pk_mul_f32 v[8:9], v[40:41], v[8:9]
	s_nop 0
	v_bfe_u32 v37, v8, 16, 1
	v_add3_u32 v8, v8, v37, s3
	v_bfe_u32 v37, v9, 16, 1
	v_pk_mul_f32 v[10:11], v[42:43], v[10:11]
	v_lshrrev_b32_e32 v8, 16, v8
	v_add3_u32 v9, v9, v37, s3
	v_and_or_b32 v8, v9, s29, v8
	v_bfe_u32 v9, v10, 16, 1
	v_add3_u32 v9, v10, v9, s3
	v_bfe_u32 v10, v11, 16, 1
	v_lshrrev_b32_e32 v9, 16, v9
	v_add3_u32 v10, v11, v10, s3
	v_and_or_b32 v9, v10, s29, v9
	global_store_dwordx2 v[38:39], v[8:9], off offset:2560
	v_pk_mul_f32 v[8:9], v[0:1], v[36:37] op_sel_hi:[1,0]
	v_pk_mul_f32 v[10:11], v[2:3], v[36:37] op_sel_hi:[1,0]
	ds_read_b128 v[0:3], v59 offset:47104
	v_pk_mul_f32 v[4:5], v[36:37], v[4:5] op_sel_hi:[0,1]
	v_pk_mul_f32 v[6:7], v[36:37], v[6:7] op_sel_hi:[0,1]
	s_waitcnt lgkmcnt(0)
	v_pk_mul_f32 v[0:1], v[8:9], v[0:1]
	s_nop 0
	v_bfe_u32 v8, v0, 16, 1
	v_add3_u32 v0, v0, v8, s3
	v_bfe_u32 v8, v1, 16, 1
	v_pk_mul_f32 v[2:3], v[10:11], v[2:3]
	v_lshrrev_b32_e32 v0, 16, v0
	v_add3_u32 v1, v1, v8, s3
	v_and_or_b32 v0, v1, s29, v0
	v_bfe_u32 v1, v2, 16, 1
	v_add3_u32 v1, v2, v1, s3
	v_bfe_u32 v2, v3, 16, 1
	v_lshrrev_b32_e32 v1, 16, v1
	v_add3_u32 v2, v3, v2, s3
	v_and_or_b32 v1, v2, s29, v1
	global_store_dwordx2 v[38:39], v[0:1], off offset:3072
	ds_read_b128 v[0:3], v59 offset:48128
	s_waitcnt lgkmcnt(0)
	v_pk_mul_f32 v[0:1], v[4:5], v[0:1]
	s_nop 0
	v_bfe_u32 v4, v0, 16, 1
	v_add3_u32 v0, v0, v4, s3
	v_bfe_u32 v4, v1, 16, 1
	v_pk_mul_f32 v[2:3], v[6:7], v[2:3]
	v_lshrrev_b32_e32 v0, 16, v0
	v_add3_u32 v1, v1, v4, s3
	v_and_or_b32 v0, v1, s29, v0
	v_bfe_u32 v1, v2, 16, 1
	v_add3_u32 v1, v2, v1, s3
	v_bfe_u32 v2, v3, 16, 1
	v_lshrrev_b32_e32 v1, 16, v1
	v_add3_u32 v2, v3, v2, s3
	v_and_or_b32 v1, v2, s29, v1
	global_store_dwordx2 v[38:39], v[0:1], off offset:3584
	s_cbranch_scc1 .LBB0_1304
	s_waitcnt vmcnt(0)
	v_mov_b32_e32 v252, 0x358637bd
